# up epilogue rewritten on a transposed accumulator layout (MFMA operands swapped): conv via in-lane FMAs + permlane32_swap, f32 neighbours, per-lane weights
# speedup vs baseline: 1.0328x; 1.0320x over previous
; template <int MB, class Epi>
; DI void gemm_tile(const u16* __restrict__ A, int lda, int row0, int Mrows, const u16* __restrict__ Bt, int ldb, int K, char* smem, Epi& epi, int rot) {
;     ...
;   for (int kt = 0; kt < KT; ++kt) {
;     const bool more = (kt + 1 < KT);
;     const bool more2 = (kt + 2 < KT);
;     const int nstg = (kt + 1) & 1;
;     const char* as = As + (kt & 1) * 32768 + wm * (32 * MB) * 128;
;     const char* bs = Bs + (kt & 1) * 32768 + wn * 64 * 128;
;     int k1_ = kbase + kt + 1; if (k1_ >= KT) k1_ -= KT;
;     int k2_ = kbase + kt + 2; if (k2_ >= KT) k2_ -= KT; if (k2_ >= KT) k2_ -= KT;
; #pragma unroll
;     for (int ks = 0; ks < 3; ++ks) {
; #pragma unroll
;       for (int idx = 0; idx < 2 * MB; ++idx) {
;         const int nb = idx / MB, mb = idx % MB;
;         acc[nb][mb] = mfma32(bfr[ks & 1][nb], af[ks & 1][mb], acc[nb][mb]);
;         if (idx < MB) af[(ks + 1) & 1][idx] = *(const bf8*)(as + idx * 32 * 128 + foff[ks + 1]);
;         else if (idx < MB + 2) bfr[(ks + 1) & 1][idx - MB] = *(const bf8*)(bs + (idx - MB) * 32 * 128 + foff[ks + 1]);
;         if (more && ks < 2 && idx < 3) {
;           const int ko_ = k1_ * 64;
;           GEMM_PIECE(nstg, 3 + ks * 3 + idx)
;         }
;         __builtin_amdgcn_sched_barrier(0);
;       }
;     }
;     if (more) {
;       asm volatile("s_waitcnt vmcnt(0)" ::: "memory");
;       __syncthreads();
;       if (more2) {
;         const int ko_ = k2_ * 64;
; #pragma unroll
;         for (int pc = 0; pc < 3; ++pc) GEMM_PIECE(kt & 1, pc)
;       }
;       __builtin_amdgcn_sched_barrier(0);
;       const char* asn = As + nstg * 32768 + wm * (32 * MB) * 128;
;       const char* bsn = Bs + nstg * 32768 + wn * 64 * 128;
; #pragma unroll
;       for (int mb = 0; mb < MB; ++mb) af[0][mb] = *(const bf8*)(asn + mb * 32 * 128 + foff[0]);
; #pragma unroll
;       for (int nb = 0; nb < 2; ++nb) bfr[0][nb] = *(const bf8*)(bsn + nb * 32 * 128 + foff[0]);
;     }
; #pragma unroll
;     for (int nb = 0; nb < 2; ++nb)
; #pragma unroll
;       for (int mb = 0; mb < MB; ++mb) acc[nb][mb] = mfma32(bfr[1][nb], af[1][mb], acc[nb][mb]);
; #pragma unroll
;     for (int gk = 0; gk < 2 * MB; ++gk) {
;       __builtin_amdgcn_sched_group_barrier(0x008, 1, 0);
;       __builtin_amdgcn_sched_group_barrier(0x100, 1, 0);
;     }
;     __builtin_amdgcn_sched_barrier(0);
;   }
.LBB0_774:
	s_and_b32 s28, s18, 0x8000
	s_add_i32 s31, s17, s28
	s_add_i32 s29, s2, s28
	s_cmp_gt_i32 s25, 14
	s_cselect_b32 s27, -15, 1
	s_waitcnt lgkmcnt(1)
	v_mfma_f32_32x32x16_bf16 v[98:113], v[146:149], v[150:153], v[98:113]
	s_add_i32 s27, s27, s25
	s_lshl_b32 s36, s27, 6
	s_ashr_i32 s37, s36, 31
	s_add_i32 s18, s18, 0x8000
	v_add_u32_e32 v159, s31, v171
	s_lshl_b64 s[36:37], s[36:37], 1
	s_and_b32 s27, s18, 0x8000
	ds_read_b128 v[172:175], v159
	s_add_i32 s39, s27, s23
	v_lshl_add_u64 v[176:177], v[156:157], 0, s[36:37]
	s_mov_b32 m0, s39
	s_nop 0
	global_load_lds_dwordx4 v[176:177], off
	v_lshl_add_u64 v[184:185], v[154:155], 0, s[36:37]
	s_add_i32 s38, s27, s22
	v_mfma_f32_32x32x16_bf16 v[50:65], v[142:145], v[150:153], v[50:65]
	ds_read_b128 v[176:179], v159 offset:4096
	s_mov_b32 m0, s38
	s_nop 0
	global_load_lds_dwordx4 v[184:185], off
	v_mfma_f32_32x32x16_bf16 v[18:33], v[134:137], v[150:153], v[18:33]
	ds_read_b128 v[180:183], v159 offset:8192
	s_add_i32 s36, s38, 0x2000
	v_lshl_add_u64 v[186:187], v[184:185], 0, s[4:5]
	s_mov_b32 m0, s36
	s_nop 0
	global_load_lds_dwordx4 v[186:187], off
	v_mfma_f32_32x32x16_bf16 v[2:17], v[130:133], v[150:153], v[2:17]
	ds_read_b128 v[150:153], v159 offset:12288
	s_waitcnt lgkmcnt(4)
	v_mfma_f32_32x32x16_bf16 v[114:129], v[146:149], v[138:141], v[114:129]
	v_add_u32_e32 v159, s29, v171
	ds_read_b128 v[146:149], v159
	v_mfma_f32_32x32x16_bf16 v[82:97], v[142:145], v[138:141], v[82:97]
	ds_read_b128 v[142:145], v159 offset:4096
	v_mfma_f32_32x32x16_bf16 v[66:81], v[134:137], v[138:141], v[66:81]
	v_mfma_f32_32x32x16_bf16 v[34:49], v[130:133], v[138:141], v[34:49]
	s_waitcnt lgkmcnt(1)
	v_mfma_f32_32x32x16_bf16 v[98:113], v[172:175], v[146:149], v[98:113]
	v_add_u32_e32 v159, s31, v170
	ds_read_b128 v[130:133], v159
	s_add_i32 s36, s38, 0x4000
	v_lshl_add_u64 v[134:135], v[184:185], 0, s[6:7]
	s_mov_b32 m0, s36
	s_nop 0
	global_load_lds_dwordx4 v[134:135], off
	v_mfma_f32_32x32x16_bf16 v[50:65], v[176:179], v[146:149], v[50:65]
	ds_read_b128 v[134:137], v159 offset:4096
	s_addk_i32 s38, 0x6000
	v_lshl_add_u64 v[138:139], v[184:185], 0, s[34:35]
	s_mov_b32 m0, s38
	s_nop 0
	global_load_lds_dwordx4 v[138:139], off
	v_mfma_f32_32x32x16_bf16 v[18:33], v[180:183], v[146:149], v[18:33]
	ds_read_b128 v[138:141], v159 offset:8192
	v_mfma_f32_32x32x16_bf16 v[2:17], v[150:153], v[146:149], v[2:17]
	ds_read_b128 v[146:149], v159 offset:12288
	s_waitcnt lgkmcnt(4)
	v_mfma_f32_32x32x16_bf16 v[114:129], v[172:175], v[142:145], v[114:129]
	v_add_u32_e32 v159, s29, v170
	ds_read_b128 v[172:175], v159
	v_mfma_f32_32x32x16_bf16 v[82:97], v[176:179], v[142:145], v[82:97]
	ds_read_b128 v[176:179], v159 offset:4096
	v_mfma_f32_32x32x16_bf16 v[66:81], v[180:183], v[142:145], v[66:81]
	v_mfma_f32_32x32x16_bf16 v[34:49], v[150:153], v[142:145], v[34:49]
	s_waitcnt lgkmcnt(1)
	v_mfma_f32_32x32x16_bf16 v[98:113], v[130:133], v[172:175], v[98:113]
	v_add_u32_e32 v142, s31, v168
	ds_read_b128 v[150:153], v142
	v_mfma_f32_32x32x16_bf16 v[50:65], v[134:137], v[172:175], v[50:65]
	ds_read_b128 v[180:183], v142 offset:4096
	v_mfma_f32_32x32x16_bf16 v[18:33], v[138:141], v[172:175], v[18:33]
	ds_read_b128 v[184:187], v142 offset:8192
	v_mfma_f32_32x32x16_bf16 v[2:17], v[146:149], v[172:175], v[2:17]
	ds_read_b128 v[172:175], v142 offset:12288
	s_waitcnt lgkmcnt(4)
	v_mfma_f32_32x32x16_bf16 v[114:129], v[130:133], v[176:179], v[114:129]
	v_add_u32_e32 v142, s29, v168
	ds_read_b128 v[130:133], v142
	v_mfma_f32_32x32x16_bf16 v[82:97], v[134:137], v[176:179], v[82:97]
	ds_read_b128 v[188:191], v142 offset:4096
	v_mfma_f32_32x32x16_bf16 v[66:81], v[138:141], v[176:179], v[66:81]
	v_mfma_f32_32x32x16_bf16 v[34:49], v[146:149], v[176:179], v[34:49]
	s_cmp_gt_i32 s25, 13
	s_cselect_b32 s29, -14, 2
	s_add_i32 s29, s29, s25
	s_lshl_b32 s31, s29, 6
	s_add_i32 s36, s31, 0xfffffc00
	s_cmp_gt_i32 s29, 15
	s_cselect_b32 s36, s36, s31
	s_ashr_i32 s37, s36, 31
	s_lshl_b64 s[36:37], s[36:37], 1
	s_add_u32 s36, s84, s36
	s_addc_u32 s37, s85, s37
	s_waitcnt vmcnt(0)
	s_waitcnt lgkmcnt(0)
	s_barrier
	s_add_i32 s28, s28, s3
	v_lshl_add_u64 v[134:135], s[36:37], 0, v[0:1]
	s_mov_b32 m0, s28
	s_nop 0
	global_load_lds_dwordx4 v[134:135], off
	v_mov_b32_e32 v159, v1
	v_lshl_add_u64 v[134:135], s[36:37], 0, v[158:159]
	s_add_i32 s29, s28, 0x2000
	s_mov_b32 m0, s29
	s_nop 0
	global_load_lds_dwordx4 v[134:135], off
	v_mov_b32_e32 v161, v1
	v_lshl_add_u64 v[134:135], s[36:37], 0, v[160:161]
	s_addk_i32 s28, 0x4000
	s_mov_b32 m0, s28
	s_nop 0
	global_load_lds_dwordx4 v[134:135], off
	v_add_u32_e32 v138, s27, v164
	v_mfma_f32_32x32x16_bf16 v[98:113], v[150:153], v[130:133], v[98:113]
	ds_read_b128 v[146:149], v138
	v_mfma_f32_32x32x16_bf16 v[50:65], v[180:183], v[130:133], v[50:65]
	ds_read_b128 v[142:145], v138 offset:4096
	v_mfma_f32_32x32x16_bf16 v[18:33], v[184:187], v[130:133], v[18:33]
	ds_read_b128 v[134:137], v138 offset:8192
	v_mfma_f32_32x32x16_bf16 v[2:17], v[172:175], v[130:133], v[2:17]
	ds_read_b128 v[130:133], v138 offset:12288
	v_add_u32_e32 v138, s27, v166
	v_mfma_f32_32x32x16_bf16 v[114:129], v[150:153], v[188:191], v[114:129]
	ds_read_b128 v[150:153], v138
	v_mfma_f32_32x32x16_bf16 v[82:97], v[180:183], v[188:191], v[82:97]
	ds_read_b128 v[138:141], v138 offset:4096
	v_mfma_f32_32x32x16_bf16 v[66:81], v[184:187], v[188:191], v[66:81]
	v_mfma_f32_32x32x16_bf16 v[34:49], v[172:175], v[188:191], v[34:49]
	s_add_i32 s25, s25, 1
	s_cmp_eq_u32 s18, 0x70000
	s_cbranch_scc0 .LBB0_774
; template <int MB, class Epi>
; DI void gemm_tile(const u16* __restrict__ A, int lda, int row0, int Mrows, const u16* __restrict__ Bt, int ldb, int K, char* smem, Epi& epi, int rot) {
;     ...
;   for (int kt = 0; kt < KT; ++kt) {
;     const bool more = (kt + 1 < KT);
;     const bool more2 = (kt + 2 < KT);
;     const int nstg = (kt + 1) & 1;
;     const char* as = As + (kt & 1) * 32768 + wm * (32 * MB) * 128;
;     const char* bs = Bs + (kt & 1) * 32768 + wn * 64 * 128;
;     int k1_ = kbase + kt + 1; if (k1_ >= KT) k1_ -= KT;
;     int k2_ = kbase + kt + 2; if (k2_ >= KT) k2_ -= KT; if (k2_ >= KT) k2_ -= KT;
; #pragma unroll
;     for (int ks = 0; ks < 3; ++ks) {
; #pragma unroll
;       for (int idx = 0; idx < 2 * MB; ++idx) {
;         const int nb = idx / MB, mb = idx % MB;
;         acc[nb][mb] = mfma32(bfr[ks & 1][nb], af[ks & 1][mb], acc[nb][mb]);
;         if (idx < MB) af[(ks + 1) & 1][idx] = *(const bf8*)(as + idx * 32 * 128 + foff[ks + 1]);
;         else if (idx < MB + 2) bfr[(ks + 1) & 1][idx - MB] = *(const bf8*)(bs + (idx - MB) * 32 * 128 + foff[ks + 1]);
;         if (more && ks < 2 && idx < 3) {
;           const int ko_ = k1_ * 64;
;           GEMM_PIECE(nstg, 3 + ks * 3 + idx)
;         }
;         __builtin_amdgcn_sched_barrier(0);
;       }
;     }
;     if (more) {
;       asm volatile("s_waitcnt vmcnt(0)" ::: "memory");
;       __syncthreads();
;       if (more2) {
;         const int ko_ = k2_ * 64;
; #pragma unroll
;         for (int pc = 0; pc < 3; ++pc) GEMM_PIECE(kt & 1, pc)
;       }
;       __builtin_amdgcn_sched_barrier(0);
;       const char* asn = As + nstg * 32768 + wm * (32 * MB) * 128;
;       const char* bsn = Bs + nstg * 32768 + wn * 64 * 128;
; #pragma unroll
;       for (int mb = 0; mb < MB; ++mb) af[0][mb] = *(const bf8*)(asn + mb * 32 * 128 + foff[0]);
; #pragma unroll
;       for (int nb = 0; nb < 2; ++nb) bfr[0][nb] = *(const bf8*)(bsn + nb * 32 * 128 + foff[0]);
;     }
; #pragma unroll
;     for (int nb = 0; nb < 2; ++nb)
; #pragma unroll
;       for (int mb = 0; mb < MB; ++mb) acc[nb][mb] = mfma32(bfr[1][nb], af[1][mb], acc[nb][mb]);
; #pragma unroll
;     for (int gk = 0; gk < 2 * MB; ++gk) {
;       __builtin_amdgcn_sched_group_barrier(0x008, 1, 0);
;       __builtin_amdgcn_sched_group_barrier(0x100, 1, 0);
;     }
;     __builtin_amdgcn_sched_barrier(0);
;   }
	s_cmp_lt_i32 s19, 1
	s_cselect_b32 s18, 1, -15
	s_add_i32 s19, s19, s18
	s_waitcnt lgkmcnt(1)
	v_mfma_f32_32x32x16_bf16 v[98:113], v[146:149], v[150:153], v[98:113]
	s_lshl_b32 s18, s19, 6
	s_addk_i32 s18, 0x380
	s_ashr_i32 s19, s18, 31
	v_add_u32_e32 v0, s17, v171
	s_lshl_b64 s[18:19], s[18:19], 1
	ds_read_b128 v[158:161], v0
	v_lshl_add_u64 v[176:177], v[154:155], 0, s[18:19]
	s_add_i32 s23, s3, 0xe000
	v_lshl_add_u64 v[154:155], v[156:157], 0, s[18:19]
	s_mov_b32 m0, s23
	s_nop 0
	global_load_lds_dwordx4 v[154:155], off
	s_add_i32 s22, s3, 0x18000
	v_mfma_f32_32x32x16_bf16 v[50:65], v[142:145], v[150:153], v[50:65]
	ds_read_b128 v[154:157], v0 offset:4096
	s_mov_b32 m0, s22
	s_nop 0
	global_load_lds_dwordx4 v[176:177], off
	v_mfma_f32_32x32x16_bf16 v[18:33], v[134:137], v[150:153], v[18:33]
	ds_read_b128 v[172:175], v0 offset:8192
	s_add_i32 s18, s3, 0x1a000
	v_lshl_add_u64 v[178:179], v[176:177], 0, s[4:5]
	s_mov_b32 m0, s18
	s_nop 0
	global_load_lds_dwordx4 v[178:179], off
	v_mfma_f32_32x32x16_bf16 v[2:17], v[130:133], v[150:153], v[2:17]
	ds_read_b128 v[150:153], v0 offset:12288
	s_waitcnt lgkmcnt(4)
	v_mfma_f32_32x32x16_bf16 v[114:129], v[146:149], v[138:141], v[114:129]
	v_add_u32_e32 v178, s2, v171
	ds_read_b128 v[146:149], v178
	v_mfma_f32_32x32x16_bf16 v[82:97], v[142:145], v[138:141], v[82:97]
	ds_read_b128 v[142:145], v178 offset:4096
	v_mfma_f32_32x32x16_bf16 v[66:81], v[134:137], v[138:141], v[66:81]
	v_mfma_f32_32x32x16_bf16 v[34:49], v[130:133], v[138:141], v[34:49]
	s_waitcnt lgkmcnt(1)
	v_mfma_f32_32x32x16_bf16 v[98:113], v[158:161], v[146:149], v[98:113]
	v_add_u32_e32 v179, s17, v170
	ds_read_b128 v[130:133], v179
	s_add_i32 s18, s3, 0x1c000
	v_lshl_add_u64 v[134:135], v[176:177], 0, s[6:7]
	s_mov_b32 m0, s18
	s_nop 0
	global_load_lds_dwordx4 v[134:135], off
	v_mfma_f32_32x32x16_bf16 v[50:65], v[154:157], v[146:149], v[50:65]
	ds_read_b128 v[134:137], v179 offset:4096
	s_add_i32 s3, s3, 0x1e000
	v_lshl_add_u64 v[138:139], v[176:177], 0, s[34:35]
	s_mov_b32 m0, s3
	s_nop 0
	global_load_lds_dwordx4 v[138:139], off
	v_mfma_f32_32x32x16_bf16 v[18:33], v[172:175], v[146:149], v[18:33]
	ds_read_b128 v[138:141], v179 offset:8192
	v_mfma_f32_32x32x16_bf16 v[2:17], v[150:153], v[146:149], v[2:17]
	ds_read_b128 v[146:149], v179 offset:12288
	s_waitcnt lgkmcnt(4)
	v_mfma_f32_32x32x16_bf16 v[114:129], v[158:161], v[142:145], v[114:129]
	v_add_u32_e32 v176, s2, v170
	ds_read_b128 v[158:161], v176
	v_mfma_f32_32x32x16_bf16 v[82:97], v[154:157], v[142:145], v[82:97]
	ds_read_b128 v[154:157], v176 offset:4096
	v_mfma_f32_32x32x16_bf16 v[66:81], v[172:175], v[142:145], v[66:81]
	v_mfma_f32_32x32x16_bf16 v[34:49], v[150:153], v[142:145], v[34:49]
	s_waitcnt lgkmcnt(1)
	v_mfma_f32_32x32x16_bf16 v[98:113], v[130:133], v[158:161], v[98:113]
	v_add_u32_e32 v174, s17, v168
	ds_read_b128 v[142:145], v174
	v_mfma_f32_32x32x16_bf16 v[50:65], v[134:137], v[158:161], v[50:65]
	ds_read_b128 v[150:153], v174 offset:4096
	v_mfma_f32_32x32x16_bf16 v[18:33], v[138:141], v[158:161], v[18:33]
	ds_read_b128 v[170:173], v174 offset:8192
	v_mfma_f32_32x32x16_bf16 v[2:17], v[146:149], v[158:161], v[2:17]
	ds_read_b128 v[158:161], v174 offset:12288
	s_waitcnt lgkmcnt(4)
	v_mfma_f32_32x32x16_bf16 v[114:129], v[130:133], v[154:157], v[114:129]
	v_add_u32_e32 v168, s2, v168
	ds_read_b128 v[130:133], v168
	v_mfma_f32_32x32x16_bf16 v[82:97], v[134:137], v[154:157], v[82:97]
	ds_read_b128 v[134:137], v168 offset:4096
	v_mfma_f32_32x32x16_bf16 v[66:81], v[138:141], v[154:157], v[66:81]
	v_mfma_f32_32x32x16_bf16 v[34:49], v[146:149], v[154:157], v[34:49]
	s_waitcnt vmcnt(0)
	s_waitcnt lgkmcnt(0)
	s_barrier
	v_mfma_f32_32x32x16_bf16 v[98:113], v[142:145], v[130:133], v[98:113]
	ds_read_b128 v[138:141], v164 offset:32768
	v_mfma_f32_32x32x16_bf16 v[50:65], v[150:153], v[130:133], v[50:65]
	ds_read_b128 v[146:149], v164 offset:36864
	v_mfma_f32_32x32x16_bf16 v[18:33], v[170:173], v[130:133], v[18:33]
	ds_read_b128 v[154:157], v164 offset:40960
	v_mfma_f32_32x32x16_bf16 v[2:17], v[158:161], v[130:133], v[2:17]
	ds_read_b128 v[130:133], v164 offset:45056
	v_mfma_f32_32x32x16_bf16 v[114:129], v[142:145], v[134:137], v[114:129]
	ds_read_b128 v[142:145], v166 offset:32768
	v_mfma_f32_32x32x16_bf16 v[82:97], v[150:153], v[134:137], v[82:97]
	ds_read_b128 v[150:153], v166 offset:36864
	v_mfma_f32_32x32x16_bf16 v[66:81], v[170:173], v[134:137], v[66:81]
	v_mfma_f32_32x32x16_bf16 v[34:49], v[158:161], v[134:137], v[34:49]
	s_waitcnt lgkmcnt(1)
	v_mfma_f32_32x32x16_bf16 v[98:113], v[138:141], v[142:145], v[98:113]
	ds_read_b128 v[134:137], v0 offset:32768
	v_mfma_f32_32x32x16_bf16 v[50:65], v[146:149], v[142:145], v[50:65]
	ds_read_b128 v[158:161], v0 offset:36864
	v_mfma_f32_32x32x16_bf16 v[18:33], v[154:157], v[142:145], v[18:33]
	ds_read_b128 v[170:173], v0 offset:40960
	v_mfma_f32_32x32x16_bf16 v[2:17], v[130:133], v[142:145], v[2:17]
	ds_read_b128 v[142:145], v0 offset:45056
	s_waitcnt lgkmcnt(4)
	v_mfma_f32_32x32x16_bf16 v[114:129], v[138:141], v[150:153], v[114:129]
	ds_read_b128 v[138:141], v178 offset:32768
	v_mfma_f32_32x32x16_bf16 v[82:97], v[146:149], v[150:153], v[82:97]
	ds_read_b128 v[146:149], v178 offset:36864
	v_mfma_f32_32x32x16_bf16 v[66:81], v[154:157], v[150:153], v[66:81]
	v_mfma_f32_32x32x16_bf16 v[34:49], v[130:133], v[150:153], v[34:49]
	s_waitcnt lgkmcnt(1)
	v_mfma_f32_32x32x16_bf16 v[98:113], v[134:137], v[138:141], v[98:113]
	ds_read_b128 v[130:133], v179 offset:32768
	v_mfma_f32_32x32x16_bf16 v[50:65], v[158:161], v[138:141], v[50:65]
	ds_read_b128 v[150:153], v179 offset:36864
	v_mfma_f32_32x32x16_bf16 v[18:33], v[170:173], v[138:141], v[18:33]
	ds_read_b128 v[154:157], v179 offset:40960
	v_mfma_f32_32x32x16_bf16 v[2:17], v[142:145], v[138:141], v[2:17]
	ds_read_b128 v[138:141], v179 offset:45056
	s_waitcnt lgkmcnt(4)
; DI int crow(int i, int h) { return (i & 3) + 8 * (i >> 2) + 4 * h; }
; DI f32x16 mfma32(bf8 a, bf8 b, f32x16 c) { return __builtin_amdgcn_mfma_f32_32x32x16_bf16(a, b, c, 0, 0, 0); }
; template <int MB, class Epi>
; DI void gemm_tile(const u16* __restrict__ A, int lda, int row0, int Mrows, const u16* __restrict__ Bt, int ldb, int K, char* smem, Epi& epi, int rot) {
;     ...
; #pragma unroll
;     for (int nb = 0; nb < 2; ++nb)
; #pragma unroll
;       for (int mb = 0; mb < MB; ++mb) acc[nb][mb] = mfma32(bfr[1][nb], af[1][mb], acc[nb][mb]);
; #pragma unroll
;     for (int gk = 0; gk < 2 * MB; ++gk) {
;       __builtin_amdgcn_sched_group_barrier(0x008, 1, 0);
;       __builtin_amdgcn_sched_group_barrier(0x100, 1, 0);
;     }
;     __builtin_amdgcn_sched_barrier(0);
;   }
;   DI void operator()(f32x16 (&acc)[2][4], int wm, int wn, int r, int h) {
;     float* eb = edge + ((wm * 4 + wn) * 2) * 64;
;     if (r == 0) {
; #pragma unroll
;       for (int nb = 0; nb < 2; ++nb)
; #pragma unroll
;         for (int i = 0; i < 16; ++i) eb[nb * 32 + crow(i, h)] = acc[nb][0][i];
;     }
;     if (r == 31) {
; #pragma unroll
;       for (int nb = 0; nb < 2; ++nb)
; #pragma unroll
;         for (int i = 0; i < 16; ++i) eb[64 + nb * 32 + crow(i, h)] = acc[nb][3][i];
;     }
;     __syncthreads();
;     const float* ob = edge + (((wm ^ 1) * 4 + wn) * 2) * 64 + (wm == 0 ? 0 : 64);
;     const int sp = (h << 5) | ((r - 1) & 31), sn = (h << 5) | ((r + 1) & 31);
;     const int Rb = row0 + wm * 128 + r;
;     u16* ost = ostage + (wm * 4 + wn) * (128 * 40);
;     float pm[4], nm[4];
; #pragma unroll
;     for (int mb = 0; mb < 4; ++mb) {
;       const int R = Rb + mb * 32;
;       const bool lat = R < NLAT;
;       const int tt = lat ? (R & 2047) : ((R - NLAT) & 255);
;       pm[mb] = (tt == 0) ? 0.f : 1.f;
;       nm[mb] = (tt == (lat ? 2047 : 255)) ? 0.f : 1.f;
;     }
	v_mfma_f32_32x32x16_bf16 v[114:129], v[134:137], v[146:149], v[114:129]
	ds_read_b128 v[134:137], v176 offset:32768
	v_mfma_f32_32x32x16_bf16 v[82:97], v[158:161], v[146:149], v[82:97]
	ds_read_b128 v[158:161], v176 offset:36864
	v_mfma_f32_32x32x16_bf16 v[66:81], v[170:173], v[146:149], v[66:81]
	v_mfma_f32_32x32x16_bf16 v[34:49], v[142:145], v[146:149], v[34:49]
	s_waitcnt lgkmcnt(1)
	v_mfma_f32_32x32x16_bf16 v[98:113], v[130:133], v[134:137], v[98:113]
	ds_read_b128 v[142:145], v174 offset:32768
	v_mfma_f32_32x32x16_bf16 v[50:65], v[150:153], v[134:137], v[50:65]
	ds_read_b128 v[146:149], v174 offset:36864
	v_mfma_f32_32x32x16_bf16 v[18:33], v[154:157], v[134:137], v[18:33]
	ds_read_b128 v[170:173], v174 offset:40960
	v_mfma_f32_32x32x16_bf16 v[2:17], v[138:141], v[134:137], v[2:17]
	ds_read_b128 v[134:137], v174 offset:45056
	s_waitcnt lgkmcnt(4)
	v_mfma_f32_32x32x16_bf16 v[114:129], v[130:133], v[158:161], v[114:129]
	ds_read_b128 v[130:133], v168 offset:32768
	v_mfma_f32_32x32x16_bf16 v[82:97], v[150:153], v[158:161], v[82:97]
	ds_read_b128 v[150:153], v168 offset:36864
	v_mfma_f32_32x32x16_bf16 v[66:81], v[154:157], v[158:161], v[66:81]
	v_mfma_f32_32x32x16_bf16 v[34:49], v[138:141], v[158:161], v[34:49]
	s_waitcnt lgkmcnt(1)
	v_mfma_f32_32x32x16_bf16 v[98:113], v[142:145], v[130:133], v[98:113]
	v_mfma_f32_32x32x16_bf16 v[50:65], v[146:149], v[130:133], v[50:65]
	v_mfma_f32_32x32x16_bf16 v[18:33], v[170:173], v[130:133], v[18:33]
	v_mfma_f32_32x32x16_bf16 v[2:17], v[134:137], v[130:133], v[2:17]
	s_waitcnt lgkmcnt(0)
	v_mfma_f32_32x32x16_bf16 v[114:129], v[142:145], v[150:153], v[114:129]
	v_mfma_f32_32x32x16_bf16 v[82:97], v[146:149], v[150:153], v[82:97]
	v_mfma_f32_32x32x16_bf16 v[66:81], v[170:173], v[150:153], v[66:81]
	v_mfma_f32_32x32x16_bf16 v[34:49], v[134:137], v[150:153], v[34:49]
	s_nop 7
	s_nop 7
	s_lshl_b32 s2, s15, 2
	s_or_b32 s17, s2, s16
	v_lshlrev_b32_e32 v225, 2, v167
	s_lshl_b32 s2, s48, 9
	s_lshl_b32 s3, s16, 7
	s_add_i32 s2, s2, s3
	v_add_u32_e32 v227, s2, v225
	v_add_u32_e32 v217, 0x2c00, v227
	global_load_dword v171, v227, s[40:41]
	global_load_dword v170, v227, s[44:45]
	global_load_dword v173, v227, s[46:47]
	global_load_dword v172, v227, s[42:43]
	global_load_dword v175, v217, s[40:41]
	global_load_dword v174, v217, s[44:45]
	global_load_dword v177, v217, s[46:47]
	global_load_dword v176, v217, s[42:43]
	s_lshl_b32 s3, s17, 9
	s_xor_b32 s2, s3, 0x800
	s_add_i32 s3, s3, 0x20000
	s_add_i32 s2, s2, 0x20000
	v_add_u32_e32 v226, s2, v225
	v_add_u32_e32 v225, s3, v225
	s_mov_b32 exec_hi, 0
	ds_write_b32 v225, v98
	ds_write_b32 v225, v114 offset:128
	s_mov_b64 exec, -1
	s_mov_b32 exec_lo, 0
	ds_write_b32 v225, v17 offset:256
	ds_write_b32 v225, v49 offset:384
	s_mov_b64 exec, -1
	s_mul_i32 s0, s17, 0x2800
	v_mul_u32_u24_e32 v224, 0x140, v169
	v_lshl_add_u32 v224, v167, 1, v224
	v_add_u32_e32 v224, s0, v224
	v_mov_b32_e32 v178, 0xbdd2d3e8
	v_mov_b32_e32 v180, 0xc0135761
	v_mov_b32_e32 v182, 1.0
	s_lshl_b32 s2, s15, 7
	s_add_i32 s2, s2, s14
	s_add_i32 s3, s2, 0x7f
	s_and_b32 s3, s3, 0xffffff00
	s_sub_i32 s37, s3, s2
	s_mov_b32 s36, -1
	s_cmp_lt_i32 s37, 1
	s_cbranch_scc1 .Lupe_nb
	s_cmp_ge_i32 s3, 0x8000
	s_cbranch_scc1 .Lupe_yes
	s_and_b32 s100, s3, 0x7ff
	s_cmp_lg_u32 s100, 0
	s_cbranch_scc1 .Lupe_nb
.Lupe_yes:
	s_add_i32 s37, s37, -1
	s_lshr_b32 s36, s37, 3
	s_lshl_b32 s36, s36, 1
	s_bfe_u32 s100, s37, 0x10001
	s_or_b32 s36, s36, s100
	s_bfe_u32 s100, s37, 0x10002
	s_cmp_eq_u32 s100, 0
	s_cselect_b32 s38, 0, -1
	s_cselect_b32 s39, -1, 0
.Lupe_nb:
	s_waitcnt lgkmcnt(0)
	s_barrier
	s_waitcnt vmcnt(0)
	s_cmp_lt_i32 s36, 0
	s_cbranch_scc0 .Lupe_slow
	v_mov_b32_e32 v184, v50
	v_mov_b32_e32 v185, v82
	v_pk_fma_f32 v[130:131], v[98:99], v[170:171], v[172:173] op_sel_hi:[1,0,0]
	v_pk_fma_f32 v[132:133], v[100:101], v[170:171], v[172:173] op_sel_hi:[1,0,0]
	v_pk_fma_f32 v[134:135], v[102:103], v[170:171], v[172:173] op_sel_hi:[1,0,0]
	v_pk_fma_f32 v[136:137], v[104:105], v[170:171], v[172:173] op_sel_hi:[1,0,0]
	v_pk_fma_f32 v[138:139], v[106:107], v[170:171], v[172:173] op_sel_hi:[1,0,0]
	v_pk_fma_f32 v[140:141], v[108:109], v[170:171], v[172:173] op_sel_hi:[1,0,0]
	v_pk_fma_f32 v[142:143], v[110:111], v[170:171], v[172:173] op_sel_hi:[1,0,0]
	v_pk_fma_f32 v[144:145], v[112:113], v[170:171], v[172:173] op_sel_hi:[1,0,0]
	v_pk_fma_f32 v[146:147], v[114:115], v[174:175], v[176:177] op_sel_hi:[1,0,0]
	v_pk_fma_f32 v[148:149], v[116:117], v[174:175], v[176:177] op_sel_hi:[1,0,0]
	v_pk_fma_f32 v[150:151], v[118:119], v[174:175], v[176:177] op_sel_hi:[1,0,0]
	v_pk_fma_f32 v[152:153], v[120:121], v[174:175], v[176:177] op_sel_hi:[1,0,0]
	v_pk_fma_f32 v[154:155], v[122:123], v[174:175], v[176:177] op_sel_hi:[1,0,0]
	v_pk_fma_f32 v[156:157], v[124:125], v[174:175], v[176:177] op_sel_hi:[1,0,0]
	v_pk_fma_f32 v[158:159], v[126:127], v[174:175], v[176:177] op_sel_hi:[1,0,0]
	v_pk_fma_f32 v[160:161], v[128:129], v[174:175], v[176:177] op_sel_hi:[1,0,0]
	v_fmac_f32_e32 v131, v171, v98
	v_fmac_f32_e32 v130, v173, v99
	v_fmac_f32_e32 v147, v175, v114
	v_fmac_f32_e32 v146, v177, v115
	v_fmac_f32_e32 v133, v171, v100
	v_fmac_f32_e32 v132, v173, v101
	v_fmac_f32_e32 v149, v175, v116
	v_fmac_f32_e32 v148, v177, v117
	v_fmac_f32_e32 v135, v171, v102
	v_fmac_f32_e32 v134, v173, v103
	v_fmac_f32_e32 v151, v175, v118
	v_fmac_f32_e32 v150, v177, v119
	v_fmac_f32_e32 v137, v171, v104
	v_fmac_f32_e32 v136, v173, v105
	v_fmac_f32_e32 v153, v175, v120
	v_fmac_f32_e32 v152, v177, v121
	v_fmac_f32_e32 v139, v171, v106
	v_fmac_f32_e32 v138, v173, v107
	v_fmac_f32_e32 v155, v175, v122
	v_fmac_f32_e32 v154, v177, v123
	v_fmac_f32_e32 v141, v171, v108
; DI int crow(int i, int h) { return (i & 3) + 8 * (i >> 2) + 4 * h; }
;   DI void operator()(f32x16 (&acc)[2][4], int wm, int wn, int r, int h) {
;     ...
; #pragma unroll
;     for (int ig = 0; ig < 4; ++ig)
; #pragma unroll
;       for (int qp = 0; qp < 2; ++qp) {
;         const int i0 = ig * 4 + qp * 2;
;         float u[2][4][2];
; #pragma unroll
;         for (int nb = 0; nb < 2; ++nb) {
;           int xp[4];
; #pragma unroll
;           for (int mb = 0; mb < 4; ++mb) xp[mb] = (int)pack2(acc[nb][mb][i0], acc[nb][mb][i0 + 1]);
;           const float eo0 = ob[nb * 32 + crow(i0, h)], eo1 = ob[nb * 32 + crow(i0 + 1, h)];
;           float w0[2], w1[2], w2[2], bz[2];
;           {
;             const int ff = nt * 128 + wn * 32 + crow(i0, h) + nb * DFF;
;             const f32x2n a0 = *(const f32x2n*)(cw + ff), a1 = *(const f32x2n*)(cw + 2 * DFF + ff), a2 = *(const f32x2n*)(cw + 4 * DFF + ff),
;                          a3 = *(const f32x2n*)(cb + ff);
;             w0[0] = a0.x; w0[1] = a0.y; w1[0] = a1.x; w1[1] = a1.y; w2[0] = a2.x; w2[1] = a2.y; bz[0] = a3.x; bz[1] = a3.y;
;           }
;           int spm = 0;
; #pragma unroll
;           for (int mb = 0; mb < 4; ++mb) {
;             const int spc = __builtin_amdgcn_ds_bpermute(sp << 2, xp[mb]);
;             const int snc = __builtin_amdgcn_ds_bpermute(sn << 2, xp[mb]);
;             const int snn = (mb < 3) ? __builtin_amdgcn_ds_bpermute(sn << 2, xp[mb < 3 ? mb + 1 : 3]) : 0;
;             const int pv = (mb > 0) ? ((r == 0) ? spm : spc) : spc;
;             const int nv = (mb < 3) ? ((r == 31) ? snn : snc) : snc;
;             float prev0 = __int_as_float(pv << 16), prev1 = __int_as_float(pv & 0xffff0000);
;             float next0 = __int_as_float(nv << 16), next1 = __int_as_float(nv & 0xffff0000);
;             if (mb == 0 && r == 0) { prev0 = eo0; prev1 = eo1; }
;             if (mb == 3 && r == 31) { next0 = eo0; next1 = eo1; }
;             spm = spc;
;             prev0 *= pm[mb]; prev1 *= pm[mb];
;             next0 *= nm[mb]; next1 *= nm[mb];
;             u[nb][mb][0] = w0[0] * prev0 + w1[0] * acc[nb][mb][i0] + w2[0] * next0 + bz[0];
;             u[nb][mb][1] = w0[1] * prev1 + w1[1] * acc[nb][mb][i0 + 1] + w2[1] * next1 + bz[1];
;           }
;         }
; #pragma unroll
;         for (int mb = 0; mb < 4; ++mb)
;           *(unsigned*)(ost + (mb * 32 + r) * 40 + ig * 8 + h * 4 + qp * 2) =
	v_fmac_f32_e32 v140, v173, v109
	v_fmac_f32_e32 v157, v175, v124
	v_fmac_f32_e32 v156, v177, v125
	v_fmac_f32_e32 v143, v171, v110
	v_fmac_f32_e32 v142, v173, v111
	v_fmac_f32_e32 v159, v175, v126
	v_fmac_f32_e32 v158, v177, v127
	v_fmac_f32_e32 v145, v171, v112
	v_fmac_f32_e32 v144, v173, v113
	v_fmac_f32_e32 v161, v175, v128
	v_fmac_f32_e32 v160, v177, v129
	v_permlane32_swap_b32_e32 v98, v101
	v_permlane32_swap_b32_e32 v102, v105
	v_permlane32_swap_b32_e32 v106, v109
	v_permlane32_swap_b32_e32 v110, v113
	v_permlane32_swap_b32_e32 v114, v117
	v_permlane32_swap_b32_e32 v118, v121
	v_permlane32_swap_b32_e32 v122, v125
	v_permlane32_swap_b32_e32 v126, v129
	v_permlane32_swap_b32_e32 v101, v102
	v_permlane32_swap_b32_e32 v105, v106
	v_permlane32_swap_b32_e32 v109, v110
	v_permlane32_swap_b32_e32 v117, v118
	v_permlane32_swap_b32_e32 v121, v122
	v_permlane32_swap_b32_e32 v125, v126
	v_permlane32_swap_b32_e32 v113, v184
	v_permlane32_swap_b32_e32 v129, v185
	s_mov_b32 exec_hi, 0
	ds_read_b32 v98, v226 offset:256
	ds_read_b32 v114, v226 offset:384
	s_mov_b64 exec, -1
	v_fmac_f32_e32 v131, v173, v100
	v_fmac_f32_e32 v132, v171, v99
	v_fmac_f32_e32 v135, v173, v104
	v_fmac_f32_e32 v136, v171, v103
	v_fmac_f32_e32 v139, v173, v108
	v_fmac_f32_e32 v140, v171, v107
	v_fmac_f32_e32 v143, v173, v112
	v_fmac_f32_e32 v144, v171, v111
	v_fmac_f32_e32 v147, v177, v116
	v_fmac_f32_e32 v148, v175, v115
	v_fmac_f32_e32 v151, v177, v120
	v_fmac_f32_e32 v152, v175, v119
	v_fmac_f32_e32 v155, v177, v124
	v_fmac_f32_e32 v156, v175, v123
	v_fmac_f32_e32 v159, v177, v128
	v_fmac_f32_e32 v160, v175, v127
	s_waitcnt lgkmcnt(0)
	v_fmac_f32_e32 v130, v171, v98
	v_fmac_f32_e32 v133, v173, v101
	v_fmac_f32_e32 v134, v171, v102
	v_fmac_f32_e32 v137, v173, v105
	v_fmac_f32_e32 v138, v171, v106
	v_fmac_f32_e32 v141, v173, v109
	v_fmac_f32_e32 v142, v171, v110
	v_fmac_f32_e32 v145, v173, v113
	v_fmac_f32_e32 v146, v175, v114
	v_fmac_f32_e32 v149, v177, v117
	v_fmac_f32_e32 v150, v175, v118
	v_fmac_f32_e32 v153, v177, v121
	v_fmac_f32_e32 v154, v175, v122
	v_fmac_f32_e32 v157, v177, v125
	v_fmac_f32_e32 v158, v175, v126
	v_fmac_f32_e32 v161, v177, v129
	v_pk_mul_f32 v[188:189], v[146:147], v[146:147]
	v_pk_mul_f32 v[190:191], v[148:149], v[148:149]
	v_pk_mul_f32 v[192:193], v[150:151], v[150:151]
	v_pk_mul_f32 v[194:195], v[152:153], v[152:153]
	v_pk_mul_f32 v[196:197], v[154:155], v[154:155]
	v_pk_mul_f32 v[218:219], v[156:157], v[156:157]
	v_pk_mul_f32 v[220:221], v[158:159], v[158:159]
	v_pk_mul_f32 v[222:223], v[160:161], v[160:161]
	v_pk_fma_f32 v[188:189], v[188:189], v[178:179], v[180:181] op_sel_hi:[1,0,0]
	v_pk_fma_f32 v[190:191], v[190:191], v[178:179], v[180:181] op_sel_hi:[1,0,0]
	v_pk_fma_f32 v[192:193], v[192:193], v[178:179], v[180:181] op_sel_hi:[1,0,0]
	v_pk_fma_f32 v[194:195], v[194:195], v[178:179], v[180:181] op_sel_hi:[1,0,0]
	v_pk_fma_f32 v[196:197], v[196:197], v[178:179], v[180:181] op_sel_hi:[1,0,0]
	v_pk_fma_f32 v[218:219], v[218:219], v[178:179], v[180:181] op_sel_hi:[1,0,0]
	v_pk_fma_f32 v[220:221], v[220:221], v[178:179], v[180:181] op_sel_hi:[1,0,0]
	v_pk_fma_f32 v[222:223], v[222:223], v[178:179], v[180:181] op_sel_hi:[1,0,0]
	v_pk_mul_f32 v[188:189], v[146:147], v[188:189]
	v_pk_mul_f32 v[190:191], v[148:149], v[190:191]
	v_pk_mul_f32 v[192:193], v[150:151], v[192:193]
	v_pk_mul_f32 v[194:195], v[152:153], v[194:195]
	v_pk_mul_f32 v[196:197], v[154:155], v[196:197]
	v_pk_mul_f32 v[218:219], v[156:157], v[218:219]
	v_pk_mul_f32 v[220:221], v[158:159], v[220:221]
	v_pk_mul_f32 v[222:223], v[160:161], v[222:223]
	v_exp_f32_e32 v188, v188
	v_exp_f32_e32 v189, v189
	v_exp_f32_e32 v190, v190
	v_exp_f32_e32 v191, v191
	v_exp_f32_e32 v192, v192
	v_exp_f32_e32 v193, v193
	v_exp_f32_e32 v194, v194
	v_exp_f32_e32 v195, v195
	v_exp_f32_e32 v196, v196
	v_exp_f32_e32 v197, v197
	v_exp_f32_e32 v218, v218
	v_exp_f32_e32 v219, v219
	v_exp_f32_e32 v220, v220
	v_exp_f32_e32 v221, v221
	v_exp_f32_e32 v222, v222
	v_exp_f32_e32 v223, v223
	v_pk_add_f32 v[188:189], v[188:189], v[182:183] op_sel_hi:[1,0]
	v_pk_add_f32 v[190:191], v[190:191], v[182:183] op_sel_hi:[1,0]
	v_pk_add_f32 v[192:193], v[192:193], v[182:183] op_sel_hi:[1,0]
	v_pk_add_f32 v[194:195], v[194:195], v[182:183] op_sel_hi:[1,0]
	v_pk_add_f32 v[196:197], v[196:197], v[182:183] op_sel_hi:[1,0]
	v_pk_add_f32 v[218:219], v[218:219], v[182:183] op_sel_hi:[1,0]
	v_pk_add_f32 v[220:221], v[220:221], v[182:183] op_sel_hi:[1,0]
	v_pk_add_f32 v[222:223], v[222:223], v[182:183] op_sel_hi:[1,0]
	v_rcp_f32_e32 v188, v188
	v_rcp_f32_e32 v189, v189
	v_rcp_f32_e32 v190, v190
	v_rcp_f32_e32 v191, v191
	v_rcp_f32_e32 v192, v192
	v_rcp_f32_e32 v193, v193
	v_rcp_f32_e32 v194, v194
	v_rcp_f32_e32 v195, v195
	v_rcp_f32_e32 v196, v196
	v_rcp_f32_e32 v197, v197
	v_rcp_f32_e32 v218, v218
	v_rcp_f32_e32 v219, v219
	v_rcp_f32_e32 v220, v220
	v_rcp_f32_e32 v221, v221
	v_rcp_f32_e32 v222, v222
	v_rcp_f32_e32 v223, v223
	v_pk_mul_f32 v[188:189], v[146:147], v[188:189]
	v_pk_mul_f32 v[190:191], v[148:149], v[190:191]
	v_pk_mul_f32 v[192:193], v[150:151], v[192:193]
	v_pk_mul_f32 v[194:195], v[152:153], v[194:195]
	v_pk_mul_f32 v[196:197], v[154:155], v[196:197]
	v_pk_mul_f32 v[218:219], v[156:157], v[218:219]
	v_pk_mul_f32 v[220:221], v[158:159], v[220:221]
	v_pk_mul_f32 v[222:223], v[160:161], v[222:223]
	v_pk_mul_f32 v[188:189], v[188:189], v[130:131]
	v_pk_mul_f32 v[190:191], v[190:191], v[132:133]
	v_pk_mul_f32 v[192:193], v[192:193], v[134:135]
	v_pk_mul_f32 v[194:195], v[194:195], v[136:137]
	v_pk_mul_f32 v[196:197], v[196:197], v[138:139]
	v_pk_mul_f32 v[218:219], v[218:219], v[140:141]
	v_pk_mul_f32 v[220:221], v[220:221], v[142:143]
; DI int crow(int i, int h) { return (i & 3) + 8 * (i >> 2) + 4 * h; }
;   DI void operator()(f32x16 (&acc)[2][4], int wm, int wn, int r, int h) {
;     ...
; #pragma unroll
;     for (int ig = 0; ig < 4; ++ig)
; #pragma unroll
;       for (int qp = 0; qp < 2; ++qp) {
;         const int i0 = ig * 4 + qp * 2;
;         float u[2][4][2];
; #pragma unroll
;         for (int nb = 0; nb < 2; ++nb) {
;           int xp[4];
; #pragma unroll
;           for (int mb = 0; mb < 4; ++mb) xp[mb] = (int)pack2(acc[nb][mb][i0], acc[nb][mb][i0 + 1]);
;           const float eo0 = ob[nb * 32 + crow(i0, h)], eo1 = ob[nb * 32 + crow(i0 + 1, h)];
;           float w0[2], w1[2], w2[2], bz[2];
;           {
;             const int ff = nt * 128 + wn * 32 + crow(i0, h) + nb * DFF;
;             const f32x2n a0 = *(const f32x2n*)(cw + ff), a1 = *(const f32x2n*)(cw + 2 * DFF + ff), a2 = *(const f32x2n*)(cw + 4 * DFF + ff),
;                          a3 = *(const f32x2n*)(cb + ff);
;             w0[0] = a0.x; w0[1] = a0.y; w1[0] = a1.x; w1[1] = a1.y; w2[0] = a2.x; w2[1] = a2.y; bz[0] = a3.x; bz[1] = a3.y;
;           }
;           int spm = 0;
; #pragma unroll
;           for (int mb = 0; mb < 4; ++mb) {
;             const int spc = __builtin_amdgcn_ds_bpermute(sp << 2, xp[mb]);
;             const int snc = __builtin_amdgcn_ds_bpermute(sn << 2, xp[mb]);
;             const int snn = (mb < 3) ? __builtin_amdgcn_ds_bpermute(sn << 2, xp[mb < 3 ? mb + 1 : 3]) : 0;
;             const int pv = (mb > 0) ? ((r == 0) ? spm : spc) : spc;
;             const int nv = (mb < 3) ? ((r == 31) ? snn : snc) : snc;
;             float prev0 = __int_as_float(pv << 16), prev1 = __int_as_float(pv & 0xffff0000);
;             float next0 = __int_as_float(nv << 16), next1 = __int_as_float(nv & 0xffff0000);
;             if (mb == 0 && r == 0) { prev0 = eo0; prev1 = eo1; }
;             if (mb == 3 && r == 31) { next0 = eo0; next1 = eo1; }
;             spm = spc;
;             prev0 *= pm[mb]; prev1 *= pm[mb];
;             next0 *= nm[mb]; next1 *= nm[mb];
;             u[nb][mb][0] = w0[0] * prev0 + w1[0] * acc[nb][mb][i0] + w2[0] * next0 + bz[0];
;             u[nb][mb][1] = w0[1] * prev1 + w1[1] * acc[nb][mb][i0 + 1] + w2[1] * next1 + bz[1];
;           }
;         }
; #pragma unroll
;         for (int mb = 0; mb < 4; ++mb)
;           *(unsigned*)(ost + (mb * 32 + r) * 40 + ig * 8 + h * 4 + qp * 2) =
	v_pk_mul_f32 v[222:223], v[222:223], v[144:145]
	v_cvt_pk_bf16_f32 v188, v188, v189
	v_cvt_pk_bf16_f32 v190, v190, v191
	v_cvt_pk_bf16_f32 v192, v192, v193
	v_cvt_pk_bf16_f32 v194, v194, v195
	v_cvt_pk_bf16_f32 v196, v196, v197
	v_cvt_pk_bf16_f32 v218, v218, v219
	v_cvt_pk_bf16_f32 v220, v220, v221
	v_cvt_pk_bf16_f32 v222, v222, v223
	ds_write_b16 v224, v188 offset:0
	ds_write_b16_d16_hi v224, v188 offset:80
	ds_write_b16 v224, v190 offset:160
	ds_write_b16_d16_hi v224, v190 offset:240
	ds_write_b16 v224, v192 offset:640
	ds_write_b16_d16_hi v224, v192 offset:720
	ds_write_b16 v224, v194 offset:800
	ds_write_b16_d16_hi v224, v194 offset:880
	ds_write_b16 v224, v196 offset:1280
	ds_write_b16_d16_hi v224, v196 offset:1360
	ds_write_b16 v224, v218 offset:1440
	ds_write_b16_d16_hi v224, v218 offset:1520
	ds_write_b16 v224, v220 offset:1920
	ds_write_b16_d16_hi v224, v220 offset:2000
	ds_write_b16 v224, v222 offset:2080
	ds_write_b16_d16_hi v224, v222 offset:2160
	v_mov_b32_e32 v186, v18
	v_mov_b32_e32 v187, v66
	v_pk_fma_f32 v[130:131], v[50:51], v[170:171], v[172:173] op_sel_hi:[1,0,0]
	v_pk_fma_f32 v[132:133], v[52:53], v[170:171], v[172:173] op_sel_hi:[1,0,0]
	v_pk_fma_f32 v[134:135], v[54:55], v[170:171], v[172:173] op_sel_hi:[1,0,0]
	v_pk_fma_f32 v[136:137], v[56:57], v[170:171], v[172:173] op_sel_hi:[1,0,0]
	v_pk_fma_f32 v[138:139], v[58:59], v[170:171], v[172:173] op_sel_hi:[1,0,0]
	v_pk_fma_f32 v[140:141], v[60:61], v[170:171], v[172:173] op_sel_hi:[1,0,0]
	v_pk_fma_f32 v[142:143], v[62:63], v[170:171], v[172:173] op_sel_hi:[1,0,0]
	v_pk_fma_f32 v[144:145], v[64:65], v[170:171], v[172:173] op_sel_hi:[1,0,0]
	v_pk_fma_f32 v[146:147], v[82:83], v[174:175], v[176:177] op_sel_hi:[1,0,0]
	v_pk_fma_f32 v[148:149], v[84:85], v[174:175], v[176:177] op_sel_hi:[1,0,0]
	v_pk_fma_f32 v[150:151], v[86:87], v[174:175], v[176:177] op_sel_hi:[1,0,0]
	v_pk_fma_f32 v[152:153], v[88:89], v[174:175], v[176:177] op_sel_hi:[1,0,0]
	v_pk_fma_f32 v[154:155], v[90:91], v[174:175], v[176:177] op_sel_hi:[1,0,0]
	v_pk_fma_f32 v[156:157], v[92:93], v[174:175], v[176:177] op_sel_hi:[1,0,0]
	v_pk_fma_f32 v[158:159], v[94:95], v[174:175], v[176:177] op_sel_hi:[1,0,0]
	v_pk_fma_f32 v[160:161], v[96:97], v[174:175], v[176:177] op_sel_hi:[1,0,0]
	v_fmac_f32_e32 v131, v171, v50
	v_fmac_f32_e32 v130, v173, v51
	v_fmac_f32_e32 v147, v175, v82
	v_fmac_f32_e32 v146, v177, v83
	v_fmac_f32_e32 v133, v171, v52
	v_fmac_f32_e32 v132, v173, v53
	v_fmac_f32_e32 v149, v175, v84
	v_fmac_f32_e32 v148, v177, v85
	v_fmac_f32_e32 v135, v171, v54
	v_fmac_f32_e32 v134, v173, v55
	v_fmac_f32_e32 v151, v175, v86
	v_fmac_f32_e32 v150, v177, v87
	v_fmac_f32_e32 v137, v171, v56
	v_fmac_f32_e32 v136, v173, v57
	v_fmac_f32_e32 v153, v175, v88
	v_fmac_f32_e32 v152, v177, v89
	v_fmac_f32_e32 v139, v171, v58
	v_fmac_f32_e32 v138, v173, v59
	v_fmac_f32_e32 v155, v175, v90
	v_fmac_f32_e32 v154, v177, v91
	v_fmac_f32_e32 v141, v171, v60
	v_fmac_f32_e32 v140, v173, v61
	v_fmac_f32_e32 v157, v175, v92
	v_fmac_f32_e32 v156, v177, v93
	v_fmac_f32_e32 v143, v171, v62
	v_fmac_f32_e32 v142, v173, v63
	v_fmac_f32_e32 v159, v175, v94
	v_fmac_f32_e32 v158, v177, v95
	v_fmac_f32_e32 v145, v171, v64
	v_fmac_f32_e32 v144, v173, v65
	v_fmac_f32_e32 v161, v175, v96
	v_fmac_f32_e32 v160, v177, v97
	v_permlane32_swap_b32_e32 v50, v53
	v_permlane32_swap_b32_e32 v54, v57
	v_permlane32_swap_b32_e32 v58, v61
	v_permlane32_swap_b32_e32 v62, v65
	v_permlane32_swap_b32_e32 v82, v85
	v_permlane32_swap_b32_e32 v86, v89
	v_permlane32_swap_b32_e32 v90, v93
	v_permlane32_swap_b32_e32 v94, v97
	v_permlane32_swap_b32_e32 v53, v54
	v_permlane32_swap_b32_e32 v57, v58
	v_permlane32_swap_b32_e32 v61, v62
	v_permlane32_swap_b32_e32 v85, v86
	v_permlane32_swap_b32_e32 v89, v90
	v_permlane32_swap_b32_e32 v93, v94
	v_permlane32_swap_b32_e32 v65, v186
	v_permlane32_swap_b32_e32 v97, v187
	s_mov_b32 exec_hi, 0
	v_mov_b32_e32 v50, v184
	v_mov_b32_e32 v82, v185
	s_mov_b64 exec, -1
	v_fmac_f32_e32 v131, v173, v52
	v_fmac_f32_e32 v132, v171, v51
	v_fmac_f32_e32 v135, v173, v56
	v_fmac_f32_e32 v136, v171, v55
	v_fmac_f32_e32 v139, v173, v60
	v_fmac_f32_e32 v140, v171, v59
	v_fmac_f32_e32 v143, v173, v64
	v_fmac_f32_e32 v144, v171, v63
	v_fmac_f32_e32 v147, v177, v84
	v_fmac_f32_e32 v148, v175, v83
	v_fmac_f32_e32 v151, v177, v88
	v_fmac_f32_e32 v152, v175, v87
	v_fmac_f32_e32 v155, v177, v92
	v_fmac_f32_e32 v156, v175, v91
	v_fmac_f32_e32 v159, v177, v96
	v_fmac_f32_e32 v160, v175, v95
	v_fmac_f32_e32 v130, v171, v50
	v_fmac_f32_e32 v133, v173, v53
	v_fmac_f32_e32 v134, v171, v54
	v_fmac_f32_e32 v137, v173, v57
	v_fmac_f32_e32 v138, v171, v58
	v_fmac_f32_e32 v141, v173, v61
	v_fmac_f32_e32 v142, v171, v62
	v_fmac_f32_e32 v145, v173, v65
	v_fmac_f32_e32 v146, v175, v82
	v_fmac_f32_e32 v149, v177, v85
	v_fmac_f32_e32 v150, v175, v86
	v_fmac_f32_e32 v153, v177, v89
	v_fmac_f32_e32 v154, v175, v90
	v_fmac_f32_e32 v157, v177, v93
	v_fmac_f32_e32 v158, v175, v94
	v_fmac_f32_e32 v161, v177, v97
	v_pk_mul_f32 v[188:189], v[146:147], v[146:147]
	v_pk_mul_f32 v[190:191], v[148:149], v[148:149]
	v_pk_mul_f32 v[192:193], v[150:151], v[150:151]
	v_pk_mul_f32 v[194:195], v[152:153], v[152:153]
	v_pk_mul_f32 v[196:197], v[154:155], v[154:155]
	v_pk_mul_f32 v[218:219], v[156:157], v[156:157]
	v_pk_mul_f32 v[220:221], v[158:159], v[158:159]
	v_pk_mul_f32 v[222:223], v[160:161], v[160:161]
	v_pk_fma_f32 v[188:189], v[188:189], v[178:179], v[180:181] op_sel_hi:[1,0,0]
	v_pk_fma_f32 v[190:191], v[190:191], v[178:179], v[180:181] op_sel_hi:[1,0,0]
	v_pk_fma_f32 v[192:193], v[192:193], v[178:179], v[180:181] op_sel_hi:[1,0,0]
; DI int crow(int i, int h) { return (i & 3) + 8 * (i >> 2) + 4 * h; }
;   DI void operator()(f32x16 (&acc)[2][4], int wm, int wn, int r, int h) {
;     ...
; #pragma unroll
;     for (int ig = 0; ig < 4; ++ig)
; #pragma unroll
;       for (int qp = 0; qp < 2; ++qp) {
;         const int i0 = ig * 4 + qp * 2;
;         float u[2][4][2];
; #pragma unroll
;         for (int nb = 0; nb < 2; ++nb) {
;           int xp[4];
; #pragma unroll
;           for (int mb = 0; mb < 4; ++mb) xp[mb] = (int)pack2(acc[nb][mb][i0], acc[nb][mb][i0 + 1]);
;           const float eo0 = ob[nb * 32 + crow(i0, h)], eo1 = ob[nb * 32 + crow(i0 + 1, h)];
;           float w0[2], w1[2], w2[2], bz[2];
;           {
;             const int ff = nt * 128 + wn * 32 + crow(i0, h) + nb * DFF;
;             const f32x2n a0 = *(const f32x2n*)(cw + ff), a1 = *(const f32x2n*)(cw + 2 * DFF + ff), a2 = *(const f32x2n*)(cw + 4 * DFF + ff),
;                          a3 = *(const f32x2n*)(cb + ff);
;             w0[0] = a0.x; w0[1] = a0.y; w1[0] = a1.x; w1[1] = a1.y; w2[0] = a2.x; w2[1] = a2.y; bz[0] = a3.x; bz[1] = a3.y;
;           }
;           int spm = 0;
; #pragma unroll
;           for (int mb = 0; mb < 4; ++mb) {
;             const int spc = __builtin_amdgcn_ds_bpermute(sp << 2, xp[mb]);
;             const int snc = __builtin_amdgcn_ds_bpermute(sn << 2, xp[mb]);
;             const int snn = (mb < 3) ? __builtin_amdgcn_ds_bpermute(sn << 2, xp[mb < 3 ? mb + 1 : 3]) : 0;
;             const int pv = (mb > 0) ? ((r == 0) ? spm : spc) : spc;
;             const int nv = (mb < 3) ? ((r == 31) ? snn : snc) : snc;
;             float prev0 = __int_as_float(pv << 16), prev1 = __int_as_float(pv & 0xffff0000);
;             float next0 = __int_as_float(nv << 16), next1 = __int_as_float(nv & 0xffff0000);
;             if (mb == 0 && r == 0) { prev0 = eo0; prev1 = eo1; }
;             if (mb == 3 && r == 31) { next0 = eo0; next1 = eo1; }
;             spm = spc;
;             prev0 *= pm[mb]; prev1 *= pm[mb];
;             next0 *= nm[mb]; next1 *= nm[mb];
;             u[nb][mb][0] = w0[0] * prev0 + w1[0] * acc[nb][mb][i0] + w2[0] * next0 + bz[0];
;             u[nb][mb][1] = w0[1] * prev1 + w1[1] * acc[nb][mb][i0 + 1] + w2[1] * next1 + bz[1];
;           }
;         }
; #pragma unroll
;         for (int mb = 0; mb < 4; ++mb)
;           *(unsigned*)(ost + (mb * 32 + r) * 40 + ig * 8 + h * 4 + qp * 2) =
	v_pk_fma_f32 v[194:195], v[194:195], v[178:179], v[180:181] op_sel_hi:[1,0,0]
	v_pk_fma_f32 v[196:197], v[196:197], v[178:179], v[180:181] op_sel_hi:[1,0,0]
	v_pk_fma_f32 v[218:219], v[218:219], v[178:179], v[180:181] op_sel_hi:[1,0,0]
	v_pk_fma_f32 v[220:221], v[220:221], v[178:179], v[180:181] op_sel_hi:[1,0,0]
	v_pk_fma_f32 v[222:223], v[222:223], v[178:179], v[180:181] op_sel_hi:[1,0,0]
	v_pk_mul_f32 v[188:189], v[146:147], v[188:189]
	v_pk_mul_f32 v[190:191], v[148:149], v[190:191]
	v_pk_mul_f32 v[192:193], v[150:151], v[192:193]
	v_pk_mul_f32 v[194:195], v[152:153], v[194:195]
	v_pk_mul_f32 v[196:197], v[154:155], v[196:197]
	v_pk_mul_f32 v[218:219], v[156:157], v[218:219]
	v_pk_mul_f32 v[220:221], v[158:159], v[220:221]
	v_pk_mul_f32 v[222:223], v[160:161], v[222:223]
	v_exp_f32_e32 v188, v188
	v_exp_f32_e32 v189, v189
	v_exp_f32_e32 v190, v190
	v_exp_f32_e32 v191, v191
	v_exp_f32_e32 v192, v192
	v_exp_f32_e32 v193, v193
	v_exp_f32_e32 v194, v194
	v_exp_f32_e32 v195, v195
	v_exp_f32_e32 v196, v196
	v_exp_f32_e32 v197, v197
	v_exp_f32_e32 v218, v218
	v_exp_f32_e32 v219, v219
	v_exp_f32_e32 v220, v220
	v_exp_f32_e32 v221, v221
	v_exp_f32_e32 v222, v222
	v_exp_f32_e32 v223, v223
	v_pk_add_f32 v[188:189], v[188:189], v[182:183] op_sel_hi:[1,0]
	v_pk_add_f32 v[190:191], v[190:191], v[182:183] op_sel_hi:[1,0]
	v_pk_add_f32 v[192:193], v[192:193], v[182:183] op_sel_hi:[1,0]
	v_pk_add_f32 v[194:195], v[194:195], v[182:183] op_sel_hi:[1,0]
	v_pk_add_f32 v[196:197], v[196:197], v[182:183] op_sel_hi:[1,0]
	v_pk_add_f32 v[218:219], v[218:219], v[182:183] op_sel_hi:[1,0]
	v_pk_add_f32 v[220:221], v[220:221], v[182:183] op_sel_hi:[1,0]
	v_pk_add_f32 v[222:223], v[222:223], v[182:183] op_sel_hi:[1,0]
	v_rcp_f32_e32 v188, v188
	v_rcp_f32_e32 v189, v189
	v_rcp_f32_e32 v190, v190
	v_rcp_f32_e32 v191, v191
	v_rcp_f32_e32 v192, v192
	v_rcp_f32_e32 v193, v193
	v_rcp_f32_e32 v194, v194
	v_rcp_f32_e32 v195, v195
	v_rcp_f32_e32 v196, v196
	v_rcp_f32_e32 v197, v197
	v_rcp_f32_e32 v218, v218
	v_rcp_f32_e32 v219, v219
	v_rcp_f32_e32 v220, v220
	v_rcp_f32_e32 v221, v221
	v_rcp_f32_e32 v222, v222
	v_rcp_f32_e32 v223, v223
	v_pk_mul_f32 v[188:189], v[146:147], v[188:189]
	v_pk_mul_f32 v[190:191], v[148:149], v[190:191]
	v_pk_mul_f32 v[192:193], v[150:151], v[192:193]
	v_pk_mul_f32 v[194:195], v[152:153], v[194:195]
	v_pk_mul_f32 v[196:197], v[154:155], v[196:197]
	v_pk_mul_f32 v[218:219], v[156:157], v[218:219]
	v_pk_mul_f32 v[220:221], v[158:159], v[220:221]
	v_pk_mul_f32 v[222:223], v[160:161], v[222:223]
	v_pk_mul_f32 v[188:189], v[188:189], v[130:131]
	v_pk_mul_f32 v[190:191], v[190:191], v[132:133]
	v_pk_mul_f32 v[192:193], v[192:193], v[134:135]
	v_pk_mul_f32 v[194:195], v[194:195], v[136:137]
	v_pk_mul_f32 v[196:197], v[196:197], v[138:139]
	v_pk_mul_f32 v[218:219], v[218:219], v[140:141]
	v_pk_mul_f32 v[220:221], v[220:221], v[142:143]
	v_pk_mul_f32 v[222:223], v[222:223], v[144:145]
	v_cvt_pk_bf16_f32 v188, v188, v189
	v_cvt_pk_bf16_f32 v190, v190, v191
	v_cvt_pk_bf16_f32 v192, v192, v193
	v_cvt_pk_bf16_f32 v194, v194, v195
	v_cvt_pk_bf16_f32 v196, v196, v197
	v_cvt_pk_bf16_f32 v218, v218, v219
	v_cvt_pk_bf16_f32 v220, v220, v221
	v_cvt_pk_bf16_f32 v222, v222, v223
	ds_write_b16 v224, v188 offset:2560
	ds_write_b16_d16_hi v224, v188 offset:2640
	ds_write_b16 v224, v190 offset:2720
	ds_write_b16_d16_hi v224, v190 offset:2800
	ds_write_b16 v224, v192 offset:3200
	ds_write_b16_d16_hi v224, v192 offset:3280
	ds_write_b16 v224, v194 offset:3360
	ds_write_b16_d16_hi v224, v194 offset:3440
	ds_write_b16 v224, v196 offset:3840
	ds_write_b16_d16_hi v224, v196 offset:3920
	ds_write_b16 v224, v218 offset:4000
	ds_write_b16_d16_hi v224, v218 offset:4080
	ds_write_b16 v224, v220 offset:4480
	ds_write_b16_d16_hi v224, v220 offset:4560
	ds_write_b16 v224, v222 offset:4640
	ds_write_b16_d16_hi v224, v222 offset:4720
	v_mov_b32_e32 v184, v2
	v_mov_b32_e32 v185, v34
	v_pk_fma_f32 v[130:131], v[18:19], v[170:171], v[172:173] op_sel_hi:[1,0,0]
	v_pk_fma_f32 v[132:133], v[20:21], v[170:171], v[172:173] op_sel_hi:[1,0,0]
	v_pk_fma_f32 v[134:135], v[22:23], v[170:171], v[172:173] op_sel_hi:[1,0,0]
	v_pk_fma_f32 v[136:137], v[24:25], v[170:171], v[172:173] op_sel_hi:[1,0,0]
	v_pk_fma_f32 v[138:139], v[26:27], v[170:171], v[172:173] op_sel_hi:[1,0,0]
	v_pk_fma_f32 v[140:141], v[28:29], v[170:171], v[172:173] op_sel_hi:[1,0,0]
	v_pk_fma_f32 v[142:143], v[30:31], v[170:171], v[172:173] op_sel_hi:[1,0,0]
	v_pk_fma_f32 v[144:145], v[32:33], v[170:171], v[172:173] op_sel_hi:[1,0,0]
	v_pk_fma_f32 v[146:147], v[66:67], v[174:175], v[176:177] op_sel_hi:[1,0,0]
	v_pk_fma_f32 v[148:149], v[68:69], v[174:175], v[176:177] op_sel_hi:[1,0,0]
	v_pk_fma_f32 v[150:151], v[70:71], v[174:175], v[176:177] op_sel_hi:[1,0,0]
	v_pk_fma_f32 v[152:153], v[72:73], v[174:175], v[176:177] op_sel_hi:[1,0,0]
	v_pk_fma_f32 v[154:155], v[74:75], v[174:175], v[176:177] op_sel_hi:[1,0,0]
	v_pk_fma_f32 v[156:157], v[76:77], v[174:175], v[176:177] op_sel_hi:[1,0,0]
	v_pk_fma_f32 v[158:159], v[78:79], v[174:175], v[176:177] op_sel_hi:[1,0,0]
	v_pk_fma_f32 v[160:161], v[80:81], v[174:175], v[176:177] op_sel_hi:[1,0,0]
	v_fmac_f32_e32 v131, v171, v18
	v_fmac_f32_e32 v130, v173, v19
	v_fmac_f32_e32 v147, v175, v66
	v_fmac_f32_e32 v146, v177, v67
	v_fmac_f32_e32 v133, v171, v20
	v_fmac_f32_e32 v132, v173, v21
	v_fmac_f32_e32 v149, v175, v68
	v_fmac_f32_e32 v148, v177, v69
	v_fmac_f32_e32 v135, v171, v22
	v_fmac_f32_e32 v134, v173, v23
	v_fmac_f32_e32 v151, v175, v70
	v_fmac_f32_e32 v150, v177, v71
	v_fmac_f32_e32 v137, v171, v24
	v_fmac_f32_e32 v136, v173, v25
	v_fmac_f32_e32 v153, v175, v72
	v_fmac_f32_e32 v152, v177, v73
; DI int crow(int i, int h) { return (i & 3) + 8 * (i >> 2) + 4 * h; }
;   DI void operator()(f32x16 (&acc)[2][4], int wm, int wn, int r, int h) {
;     ...
; #pragma unroll
;     for (int ig = 0; ig < 4; ++ig)
; #pragma unroll
;       for (int qp = 0; qp < 2; ++qp) {
;         const int i0 = ig * 4 + qp * 2;
;         float u[2][4][2];
; #pragma unroll
;         for (int nb = 0; nb < 2; ++nb) {
;           int xp[4];
; #pragma unroll
;           for (int mb = 0; mb < 4; ++mb) xp[mb] = (int)pack2(acc[nb][mb][i0], acc[nb][mb][i0 + 1]);
;           const float eo0 = ob[nb * 32 + crow(i0, h)], eo1 = ob[nb * 32 + crow(i0 + 1, h)];
;           float w0[2], w1[2], w2[2], bz[2];
;           {
;             const int ff = nt * 128 + wn * 32 + crow(i0, h) + nb * DFF;
;             const f32x2n a0 = *(const f32x2n*)(cw + ff), a1 = *(const f32x2n*)(cw + 2 * DFF + ff), a2 = *(const f32x2n*)(cw + 4 * DFF + ff),
;                          a3 = *(const f32x2n*)(cb + ff);
;             w0[0] = a0.x; w0[1] = a0.y; w1[0] = a1.x; w1[1] = a1.y; w2[0] = a2.x; w2[1] = a2.y; bz[0] = a3.x; bz[1] = a3.y;
;           }
;           int spm = 0;
; #pragma unroll
;           for (int mb = 0; mb < 4; ++mb) {
;             const int spc = __builtin_amdgcn_ds_bpermute(sp << 2, xp[mb]);
;             const int snc = __builtin_amdgcn_ds_bpermute(sn << 2, xp[mb]);
;             const int snn = (mb < 3) ? __builtin_amdgcn_ds_bpermute(sn << 2, xp[mb < 3 ? mb + 1 : 3]) : 0;
;             const int pv = (mb > 0) ? ((r == 0) ? spm : spc) : spc;
;             const int nv = (mb < 3) ? ((r == 31) ? snn : snc) : snc;
;             float prev0 = __int_as_float(pv << 16), prev1 = __int_as_float(pv & 0xffff0000);
;             float next0 = __int_as_float(nv << 16), next1 = __int_as_float(nv & 0xffff0000);
;             if (mb == 0 && r == 0) { prev0 = eo0; prev1 = eo1; }
;             if (mb == 3 && r == 31) { next0 = eo0; next1 = eo1; }
;             spm = spc;
;             prev0 *= pm[mb]; prev1 *= pm[mb];
;             next0 *= nm[mb]; next1 *= nm[mb];
;             u[nb][mb][0] = w0[0] * prev0 + w1[0] * acc[nb][mb][i0] + w2[0] * next0 + bz[0];
;             u[nb][mb][1] = w0[1] * prev1 + w1[1] * acc[nb][mb][i0 + 1] + w2[1] * next1 + bz[1];
;           }
;         }
; #pragma unroll
;         for (int mb = 0; mb < 4; ++mb)
;           *(unsigned*)(ost + (mb * 32 + r) * 40 + ig * 8 + h * 4 + qp * 2) =
	v_fmac_f32_e32 v139, v171, v26
	v_fmac_f32_e32 v138, v173, v27
	v_fmac_f32_e32 v155, v175, v74
	v_fmac_f32_e32 v154, v177, v75
	v_fmac_f32_e32 v141, v171, v28
	v_fmac_f32_e32 v140, v173, v29
	v_fmac_f32_e32 v157, v175, v76
	v_fmac_f32_e32 v156, v177, v77
	v_fmac_f32_e32 v143, v171, v30
	v_fmac_f32_e32 v142, v173, v31
	v_fmac_f32_e32 v159, v175, v78
	v_fmac_f32_e32 v158, v177, v79
	v_fmac_f32_e32 v145, v171, v32
	v_fmac_f32_e32 v144, v173, v33
	v_fmac_f32_e32 v161, v175, v80
	v_fmac_f32_e32 v160, v177, v81
	v_permlane32_swap_b32_e32 v18, v21
	v_permlane32_swap_b32_e32 v22, v25
	v_permlane32_swap_b32_e32 v26, v29
	v_permlane32_swap_b32_e32 v30, v33
	v_permlane32_swap_b32_e32 v66, v69
	v_permlane32_swap_b32_e32 v70, v73
	v_permlane32_swap_b32_e32 v74, v77
	v_permlane32_swap_b32_e32 v78, v81
	v_permlane32_swap_b32_e32 v21, v22
	v_permlane32_swap_b32_e32 v25, v26
	v_permlane32_swap_b32_e32 v29, v30
	v_permlane32_swap_b32_e32 v69, v70
	v_permlane32_swap_b32_e32 v73, v74
	v_permlane32_swap_b32_e32 v77, v78
	v_permlane32_swap_b32_e32 v33, v184
	v_permlane32_swap_b32_e32 v81, v185
	s_mov_b32 exec_hi, 0
	v_mov_b32_e32 v18, v186
	v_mov_b32_e32 v66, v187
	s_mov_b64 exec, -1
	v_fmac_f32_e32 v131, v173, v20
	v_fmac_f32_e32 v132, v171, v19
	v_fmac_f32_e32 v135, v173, v24
	v_fmac_f32_e32 v136, v171, v23
	v_fmac_f32_e32 v139, v173, v28
	v_fmac_f32_e32 v140, v171, v27
	v_fmac_f32_e32 v143, v173, v32
	v_fmac_f32_e32 v144, v171, v31
	v_fmac_f32_e32 v147, v177, v68
	v_fmac_f32_e32 v148, v175, v67
	v_fmac_f32_e32 v151, v177, v72
	v_fmac_f32_e32 v152, v175, v71
	v_fmac_f32_e32 v155, v177, v76
	v_fmac_f32_e32 v156, v175, v75
	v_fmac_f32_e32 v159, v177, v80
	v_fmac_f32_e32 v160, v175, v79
	v_fmac_f32_e32 v130, v171, v18
	v_fmac_f32_e32 v133, v173, v21
	v_fmac_f32_e32 v134, v171, v22
	v_fmac_f32_e32 v137, v173, v25
	v_fmac_f32_e32 v138, v171, v26
	v_fmac_f32_e32 v141, v173, v29
	v_fmac_f32_e32 v142, v171, v30
	v_fmac_f32_e32 v145, v173, v33
	v_fmac_f32_e32 v146, v175, v66
	v_fmac_f32_e32 v149, v177, v69
	v_fmac_f32_e32 v150, v175, v70
	v_fmac_f32_e32 v153, v177, v73
	v_fmac_f32_e32 v154, v175, v74
	v_fmac_f32_e32 v157, v177, v77
	v_fmac_f32_e32 v158, v175, v78
	v_fmac_f32_e32 v161, v177, v81
	v_pk_mul_f32 v[188:189], v[146:147], v[146:147]
	v_pk_mul_f32 v[190:191], v[148:149], v[148:149]
	v_pk_mul_f32 v[192:193], v[150:151], v[150:151]
	v_pk_mul_f32 v[194:195], v[152:153], v[152:153]
	v_pk_mul_f32 v[196:197], v[154:155], v[154:155]
	v_pk_mul_f32 v[218:219], v[156:157], v[156:157]
	v_pk_mul_f32 v[220:221], v[158:159], v[158:159]
	v_pk_mul_f32 v[222:223], v[160:161], v[160:161]
	v_pk_fma_f32 v[188:189], v[188:189], v[178:179], v[180:181] op_sel_hi:[1,0,0]
	v_pk_fma_f32 v[190:191], v[190:191], v[178:179], v[180:181] op_sel_hi:[1,0,0]
	v_pk_fma_f32 v[192:193], v[192:193], v[178:179], v[180:181] op_sel_hi:[1,0,0]
	v_pk_fma_f32 v[194:195], v[194:195], v[178:179], v[180:181] op_sel_hi:[1,0,0]
	v_pk_fma_f32 v[196:197], v[196:197], v[178:179], v[180:181] op_sel_hi:[1,0,0]
	v_pk_fma_f32 v[218:219], v[218:219], v[178:179], v[180:181] op_sel_hi:[1,0,0]
	v_pk_fma_f32 v[220:221], v[220:221], v[178:179], v[180:181] op_sel_hi:[1,0,0]
	v_pk_fma_f32 v[222:223], v[222:223], v[178:179], v[180:181] op_sel_hi:[1,0,0]
	v_pk_mul_f32 v[188:189], v[146:147], v[188:189]
	v_pk_mul_f32 v[190:191], v[148:149], v[190:191]
	v_pk_mul_f32 v[192:193], v[150:151], v[192:193]
	v_pk_mul_f32 v[194:195], v[152:153], v[194:195]
	v_pk_mul_f32 v[196:197], v[154:155], v[196:197]
	v_pk_mul_f32 v[218:219], v[156:157], v[218:219]
	v_pk_mul_f32 v[220:221], v[158:159], v[220:221]
	v_pk_mul_f32 v[222:223], v[160:161], v[222:223]
	v_exp_f32_e32 v188, v188
	v_exp_f32_e32 v189, v189
	v_exp_f32_e32 v190, v190
	v_exp_f32_e32 v191, v191
	v_exp_f32_e32 v192, v192
	v_exp_f32_e32 v193, v193
	v_exp_f32_e32 v194, v194
	v_exp_f32_e32 v195, v195
	v_exp_f32_e32 v196, v196
	v_exp_f32_e32 v197, v197
	v_exp_f32_e32 v218, v218
	v_exp_f32_e32 v219, v219
	v_exp_f32_e32 v220, v220
	v_exp_f32_e32 v221, v221
	v_exp_f32_e32 v222, v222
	v_exp_f32_e32 v223, v223
	v_pk_add_f32 v[188:189], v[188:189], v[182:183] op_sel_hi:[1,0]
	v_pk_add_f32 v[190:191], v[190:191], v[182:183] op_sel_hi:[1,0]
	v_pk_add_f32 v[192:193], v[192:193], v[182:183] op_sel_hi:[1,0]
	v_pk_add_f32 v[194:195], v[194:195], v[182:183] op_sel_hi:[1,0]
	v_pk_add_f32 v[196:197], v[196:197], v[182:183] op_sel_hi:[1,0]
	v_pk_add_f32 v[218:219], v[218:219], v[182:183] op_sel_hi:[1,0]
	v_pk_add_f32 v[220:221], v[220:221], v[182:183] op_sel_hi:[1,0]
	v_pk_add_f32 v[222:223], v[222:223], v[182:183] op_sel_hi:[1,0]
	v_rcp_f32_e32 v188, v188
	v_rcp_f32_e32 v189, v189
	v_rcp_f32_e32 v190, v190
	v_rcp_f32_e32 v191, v191
	v_rcp_f32_e32 v192, v192
	v_rcp_f32_e32 v193, v193
	v_rcp_f32_e32 v194, v194
	v_rcp_f32_e32 v195, v195
	v_rcp_f32_e32 v196, v196
	v_rcp_f32_e32 v197, v197
	v_rcp_f32_e32 v218, v218
	v_rcp_f32_e32 v219, v219
	v_rcp_f32_e32 v220, v220
	v_rcp_f32_e32 v221, v221
	v_rcp_f32_e32 v222, v222
	v_rcp_f32_e32 v223, v223
	v_pk_mul_f32 v[188:189], v[146:147], v[188:189]
	v_pk_mul_f32 v[190:191], v[148:149], v[190:191]
	v_pk_mul_f32 v[192:193], v[150:151], v[192:193]
	v_pk_mul_f32 v[194:195], v[152:153], v[194:195]
	v_pk_mul_f32 v[196:197], v[154:155], v[196:197]
	v_pk_mul_f32 v[218:219], v[156:157], v[218:219]
	v_pk_mul_f32 v[220:221], v[158:159], v[220:221]
	v_pk_mul_f32 v[222:223], v[160:161], v[222:223]
	v_pk_mul_f32 v[188:189], v[188:189], v[130:131]
	v_pk_mul_f32 v[190:191], v[190:191], v[132:133]
	v_pk_mul_f32 v[192:193], v[192:193], v[134:135]
	v_pk_mul_f32 v[194:195], v[194:195], v[136:137]
	v_pk_mul_f32 v[196:197], v[196:197], v[138:139]
	v_pk_mul_f32 v[218:219], v[218:219], v[140:141]
; DI int crow(int i, int h) { return (i & 3) + 8 * (i >> 2) + 4 * h; }
;   DI void operator()(f32x16 (&acc)[2][4], int wm, int wn, int r, int h) {
;     ...
; #pragma unroll
;     for (int ig = 0; ig < 4; ++ig)
; #pragma unroll
;       for (int qp = 0; qp < 2; ++qp) {
;         const int i0 = ig * 4 + qp * 2;
;         float u[2][4][2];
; #pragma unroll
;         for (int nb = 0; nb < 2; ++nb) {
;           int xp[4];
; #pragma unroll
;           for (int mb = 0; mb < 4; ++mb) xp[mb] = (int)pack2(acc[nb][mb][i0], acc[nb][mb][i0 + 1]);
;           const float eo0 = ob[nb * 32 + crow(i0, h)], eo1 = ob[nb * 32 + crow(i0 + 1, h)];
;           float w0[2], w1[2], w2[2], bz[2];
;           {
;             const int ff = nt * 128 + wn * 32 + crow(i0, h) + nb * DFF;
;             const f32x2n a0 = *(const f32x2n*)(cw + ff), a1 = *(const f32x2n*)(cw + 2 * DFF + ff), a2 = *(const f32x2n*)(cw + 4 * DFF + ff),
;                          a3 = *(const f32x2n*)(cb + ff);
;             w0[0] = a0.x; w0[1] = a0.y; w1[0] = a1.x; w1[1] = a1.y; w2[0] = a2.x; w2[1] = a2.y; bz[0] = a3.x; bz[1] = a3.y;
;           }
;           int spm = 0;
; #pragma unroll
;           for (int mb = 0; mb < 4; ++mb) {
;             const int spc = __builtin_amdgcn_ds_bpermute(sp << 2, xp[mb]);
;             const int snc = __builtin_amdgcn_ds_bpermute(sn << 2, xp[mb]);
;             const int snn = (mb < 3) ? __builtin_amdgcn_ds_bpermute(sn << 2, xp[mb < 3 ? mb + 1 : 3]) : 0;
;             const int pv = (mb > 0) ? ((r == 0) ? spm : spc) : spc;
;             const int nv = (mb < 3) ? ((r == 31) ? snn : snc) : snc;
;             float prev0 = __int_as_float(pv << 16), prev1 = __int_as_float(pv & 0xffff0000);
;             float next0 = __int_as_float(nv << 16), next1 = __int_as_float(nv & 0xffff0000);
;             if (mb == 0 && r == 0) { prev0 = eo0; prev1 = eo1; }
;             if (mb == 3 && r == 31) { next0 = eo0; next1 = eo1; }
;             spm = spc;
;             prev0 *= pm[mb]; prev1 *= pm[mb];
;             next0 *= nm[mb]; next1 *= nm[mb];
;             u[nb][mb][0] = w0[0] * prev0 + w1[0] * acc[nb][mb][i0] + w2[0] * next0 + bz[0];
;             u[nb][mb][1] = w0[1] * prev1 + w1[1] * acc[nb][mb][i0 + 1] + w2[1] * next1 + bz[1];
;           }
;         }
; #pragma unroll
;         for (int mb = 0; mb < 4; ++mb)
;           *(unsigned*)(ost + (mb * 32 + r) * 40 + ig * 8 + h * 4 + qp * 2) =
	v_pk_mul_f32 v[220:221], v[220:221], v[142:143]
	v_pk_mul_f32 v[222:223], v[222:223], v[144:145]
	v_cvt_pk_bf16_f32 v188, v188, v189
	v_cvt_pk_bf16_f32 v190, v190, v191
	v_cvt_pk_bf16_f32 v192, v192, v193
	v_cvt_pk_bf16_f32 v194, v194, v195
	v_cvt_pk_bf16_f32 v196, v196, v197
	v_cvt_pk_bf16_f32 v218, v218, v219
	v_cvt_pk_bf16_f32 v220, v220, v221
	v_cvt_pk_bf16_f32 v222, v222, v223
	ds_write_b16 v224, v188 offset:5120
	ds_write_b16_d16_hi v224, v188 offset:5200
	ds_write_b16 v224, v190 offset:5280
	ds_write_b16_d16_hi v224, v190 offset:5360
	ds_write_b16 v224, v192 offset:5760
	ds_write_b16_d16_hi v224, v192 offset:5840
	ds_write_b16 v224, v194 offset:5920
	ds_write_b16_d16_hi v224, v194 offset:6000
	ds_write_b16 v224, v196 offset:6400
	ds_write_b16_d16_hi v224, v196 offset:6480
	ds_write_b16 v224, v218 offset:6560
	ds_write_b16_d16_hi v224, v218 offset:6640
	ds_write_b16 v224, v220 offset:7040
	ds_write_b16_d16_hi v224, v220 offset:7120
	ds_write_b16 v224, v222 offset:7200
	ds_write_b16_d16_hi v224, v222 offset:7280
	v_pk_fma_f32 v[130:131], v[2:3], v[170:171], v[172:173] op_sel_hi:[1,0,0]
	v_pk_fma_f32 v[132:133], v[4:5], v[170:171], v[172:173] op_sel_hi:[1,0,0]
	v_pk_fma_f32 v[134:135], v[6:7], v[170:171], v[172:173] op_sel_hi:[1,0,0]
	v_pk_fma_f32 v[136:137], v[8:9], v[170:171], v[172:173] op_sel_hi:[1,0,0]
	v_pk_fma_f32 v[138:139], v[10:11], v[170:171], v[172:173] op_sel_hi:[1,0,0]
	v_pk_fma_f32 v[140:141], v[12:13], v[170:171], v[172:173] op_sel_hi:[1,0,0]
	v_pk_fma_f32 v[142:143], v[14:15], v[170:171], v[172:173] op_sel_hi:[1,0,0]
	v_pk_fma_f32 v[144:145], v[16:17], v[170:171], v[172:173] op_sel_hi:[1,0,0]
	v_pk_fma_f32 v[146:147], v[34:35], v[174:175], v[176:177] op_sel_hi:[1,0,0]
	v_pk_fma_f32 v[148:149], v[36:37], v[174:175], v[176:177] op_sel_hi:[1,0,0]
	v_pk_fma_f32 v[150:151], v[38:39], v[174:175], v[176:177] op_sel_hi:[1,0,0]
	v_pk_fma_f32 v[152:153], v[40:41], v[174:175], v[176:177] op_sel_hi:[1,0,0]
	v_pk_fma_f32 v[154:155], v[42:43], v[174:175], v[176:177] op_sel_hi:[1,0,0]
	v_pk_fma_f32 v[156:157], v[44:45], v[174:175], v[176:177] op_sel_hi:[1,0,0]
	v_pk_fma_f32 v[158:159], v[46:47], v[174:175], v[176:177] op_sel_hi:[1,0,0]
	v_pk_fma_f32 v[160:161], v[48:49], v[174:175], v[176:177] op_sel_hi:[1,0,0]
	v_fmac_f32_e32 v131, v171, v2
	v_fmac_f32_e32 v130, v173, v3
	v_fmac_f32_e32 v147, v175, v34
	v_fmac_f32_e32 v146, v177, v35
	v_fmac_f32_e32 v133, v171, v4
	v_fmac_f32_e32 v132, v173, v5
	v_fmac_f32_e32 v149, v175, v36
	v_fmac_f32_e32 v148, v177, v37
	v_fmac_f32_e32 v135, v171, v6
	v_fmac_f32_e32 v134, v173, v7
	v_fmac_f32_e32 v151, v175, v38
	v_fmac_f32_e32 v150, v177, v39
	v_fmac_f32_e32 v137, v171, v8
	v_fmac_f32_e32 v136, v173, v9
	v_fmac_f32_e32 v153, v175, v40
	v_fmac_f32_e32 v152, v177, v41
	v_fmac_f32_e32 v139, v171, v10
	v_fmac_f32_e32 v138, v173, v11
	v_fmac_f32_e32 v155, v175, v42
	v_fmac_f32_e32 v154, v177, v43
	v_fmac_f32_e32 v141, v171, v12
	v_fmac_f32_e32 v140, v173, v13
	v_fmac_f32_e32 v157, v175, v44
	v_fmac_f32_e32 v156, v177, v45
	v_fmac_f32_e32 v143, v171, v14
	v_fmac_f32_e32 v142, v173, v15
	v_fmac_f32_e32 v159, v175, v46
	v_fmac_f32_e32 v158, v177, v47
	v_fmac_f32_e32 v145, v171, v16
	v_fmac_f32_e32 v144, v173, v17
	v_fmac_f32_e32 v161, v175, v48
	v_fmac_f32_e32 v160, v177, v49
	v_permlane32_swap_b32_e32 v2, v5
	v_permlane32_swap_b32_e32 v6, v9
	v_permlane32_swap_b32_e32 v10, v13
	v_permlane32_swap_b32_e32 v14, v17
	v_permlane32_swap_b32_e32 v34, v37
	v_permlane32_swap_b32_e32 v38, v41
	v_permlane32_swap_b32_e32 v42, v45
	v_permlane32_swap_b32_e32 v46, v49
	v_permlane32_swap_b32_e32 v5, v6
	v_permlane32_swap_b32_e32 v9, v10
	v_permlane32_swap_b32_e32 v13, v14
	v_permlane32_swap_b32_e32 v37, v38
	v_permlane32_swap_b32_e32 v41, v42
	v_permlane32_swap_b32_e32 v45, v46
	s_mov_b32 exec_lo, 0
	ds_read_b32 v17, v226 offset:0
	ds_read_b32 v49, v226 offset:128
	s_mov_b64 exec, -1
	s_mov_b32 exec_hi, 0
	v_mov_b32_e32 v2, v184
	v_mov_b32_e32 v34, v185
	s_mov_b64 exec, -1
	v_fmac_f32_e32 v131, v173, v4
	v_fmac_f32_e32 v132, v171, v3
	v_fmac_f32_e32 v135, v173, v8
	v_fmac_f32_e32 v136, v171, v7
	v_fmac_f32_e32 v139, v173, v12
	v_fmac_f32_e32 v140, v171, v11
	v_fmac_f32_e32 v143, v173, v16
	v_fmac_f32_e32 v144, v171, v15
	v_fmac_f32_e32 v147, v177, v36
	v_fmac_f32_e32 v148, v175, v35
	v_fmac_f32_e32 v151, v177, v40
	v_fmac_f32_e32 v152, v175, v39
	v_fmac_f32_e32 v155, v177, v44
	v_fmac_f32_e32 v156, v175, v43
	v_fmac_f32_e32 v159, v177, v48
	v_fmac_f32_e32 v160, v175, v47
	s_waitcnt lgkmcnt(0)
; DI int crow(int i, int h) { return (i & 3) + 8 * (i >> 2) + 4 * h; }
;   DI void operator()(f32x16 (&acc)[2][4], int wm, int wn, int r, int h) {
;     ...
; #pragma unroll
;     for (int ig = 0; ig < 4; ++ig)
; #pragma unroll
;       for (int qp = 0; qp < 2; ++qp) {
;         const int i0 = ig * 4 + qp * 2;
;         float u[2][4][2];
; #pragma unroll
;         for (int nb = 0; nb < 2; ++nb) {
;           int xp[4];
; #pragma unroll
;           for (int mb = 0; mb < 4; ++mb) xp[mb] = (int)pack2(acc[nb][mb][i0], acc[nb][mb][i0 + 1]);
;           const float eo0 = ob[nb * 32 + crow(i0, h)], eo1 = ob[nb * 32 + crow(i0 + 1, h)];
;           float w0[2], w1[2], w2[2], bz[2];
;           {
;             const int ff = nt * 128 + wn * 32 + crow(i0, h) + nb * DFF;
;             const f32x2n a0 = *(const f32x2n*)(cw + ff), a1 = *(const f32x2n*)(cw + 2 * DFF + ff), a2 = *(const f32x2n*)(cw + 4 * DFF + ff),
;                          a3 = *(const f32x2n*)(cb + ff);
;             w0[0] = a0.x; w0[1] = a0.y; w1[0] = a1.x; w1[1] = a1.y; w2[0] = a2.x; w2[1] = a2.y; bz[0] = a3.x; bz[1] = a3.y;
;           }
;           int spm = 0;
; #pragma unroll
;           for (int mb = 0; mb < 4; ++mb) {
;             const int spc = __builtin_amdgcn_ds_bpermute(sp << 2, xp[mb]);
;             const int snc = __builtin_amdgcn_ds_bpermute(sn << 2, xp[mb]);
;             const int snn = (mb < 3) ? __builtin_amdgcn_ds_bpermute(sn << 2, xp[mb < 3 ? mb + 1 : 3]) : 0;
;             const int pv = (mb > 0) ? ((r == 0) ? spm : spc) : spc;
;             const int nv = (mb < 3) ? ((r == 31) ? snn : snc) : snc;
;             float prev0 = __int_as_float(pv << 16), prev1 = __int_as_float(pv & 0xffff0000);
;             float next0 = __int_as_float(nv << 16), next1 = __int_as_float(nv & 0xffff0000);
;             if (mb == 0 && r == 0) { prev0 = eo0; prev1 = eo1; }
;             if (mb == 3 && r == 31) { next0 = eo0; next1 = eo1; }
;             spm = spc;
;             prev0 *= pm[mb]; prev1 *= pm[mb];
;             next0 *= nm[mb]; next1 *= nm[mb];
;             u[nb][mb][0] = w0[0] * prev0 + w1[0] * acc[nb][mb][i0] + w2[0] * next0 + bz[0];
;             u[nb][mb][1] = w0[1] * prev1 + w1[1] * acc[nb][mb][i0 + 1] + w2[1] * next1 + bz[1];
;           }
;         }
; #pragma unroll
;         for (int mb = 0; mb < 4; ++mb)
;           *(unsigned*)(ost + (mb * 32 + r) * 40 + ig * 8 + h * 4 + qp * 2) =
	v_fmac_f32_e32 v130, v171, v2
	v_fmac_f32_e32 v133, v173, v5
	v_fmac_f32_e32 v134, v171, v6
	v_fmac_f32_e32 v137, v173, v9
	v_fmac_f32_e32 v138, v171, v10
	v_fmac_f32_e32 v141, v173, v13
	v_fmac_f32_e32 v142, v171, v14
	v_fmac_f32_e32 v145, v173, v17
	v_fmac_f32_e32 v146, v175, v34
	v_fmac_f32_e32 v149, v177, v37
	v_fmac_f32_e32 v150, v175, v38
	v_fmac_f32_e32 v153, v177, v41
	v_fmac_f32_e32 v154, v175, v42
	v_fmac_f32_e32 v157, v177, v45
	v_fmac_f32_e32 v158, v175, v46
	v_fmac_f32_e32 v161, v177, v49
	v_pk_mul_f32 v[188:189], v[146:147], v[146:147]
	v_pk_mul_f32 v[190:191], v[148:149], v[148:149]
	v_pk_mul_f32 v[192:193], v[150:151], v[150:151]
	v_pk_mul_f32 v[194:195], v[152:153], v[152:153]
	v_pk_mul_f32 v[196:197], v[154:155], v[154:155]
	v_pk_mul_f32 v[218:219], v[156:157], v[156:157]
	v_pk_mul_f32 v[220:221], v[158:159], v[158:159]
	v_pk_mul_f32 v[222:223], v[160:161], v[160:161]
	v_pk_fma_f32 v[188:189], v[188:189], v[178:179], v[180:181] op_sel_hi:[1,0,0]
	v_pk_fma_f32 v[190:191], v[190:191], v[178:179], v[180:181] op_sel_hi:[1,0,0]
	v_pk_fma_f32 v[192:193], v[192:193], v[178:179], v[180:181] op_sel_hi:[1,0,0]
	v_pk_fma_f32 v[194:195], v[194:195], v[178:179], v[180:181] op_sel_hi:[1,0,0]
	v_pk_fma_f32 v[196:197], v[196:197], v[178:179], v[180:181] op_sel_hi:[1,0,0]
	v_pk_fma_f32 v[218:219], v[218:219], v[178:179], v[180:181] op_sel_hi:[1,0,0]
	v_pk_fma_f32 v[220:221], v[220:221], v[178:179], v[180:181] op_sel_hi:[1,0,0]
	v_pk_fma_f32 v[222:223], v[222:223], v[178:179], v[180:181] op_sel_hi:[1,0,0]
	v_pk_mul_f32 v[188:189], v[146:147], v[188:189]
	v_pk_mul_f32 v[190:191], v[148:149], v[190:191]
	v_pk_mul_f32 v[192:193], v[150:151], v[192:193]
	v_pk_mul_f32 v[194:195], v[152:153], v[194:195]
	v_pk_mul_f32 v[196:197], v[154:155], v[196:197]
	v_pk_mul_f32 v[218:219], v[156:157], v[218:219]
	v_pk_mul_f32 v[220:221], v[158:159], v[220:221]
	v_pk_mul_f32 v[222:223], v[160:161], v[222:223]
	v_exp_f32_e32 v188, v188
	v_exp_f32_e32 v189, v189
	v_exp_f32_e32 v190, v190
	v_exp_f32_e32 v191, v191
	v_exp_f32_e32 v192, v192
	v_exp_f32_e32 v193, v193
	v_exp_f32_e32 v194, v194
	v_exp_f32_e32 v195, v195
	v_exp_f32_e32 v196, v196
	v_exp_f32_e32 v197, v197
	v_exp_f32_e32 v218, v218
	v_exp_f32_e32 v219, v219
	v_exp_f32_e32 v220, v220
	v_exp_f32_e32 v221, v221
	v_exp_f32_e32 v222, v222
	v_exp_f32_e32 v223, v223
	v_pk_add_f32 v[188:189], v[188:189], v[182:183] op_sel_hi:[1,0]
	v_pk_add_f32 v[190:191], v[190:191], v[182:183] op_sel_hi:[1,0]
	v_pk_add_f32 v[192:193], v[192:193], v[182:183] op_sel_hi:[1,0]
	v_pk_add_f32 v[194:195], v[194:195], v[182:183] op_sel_hi:[1,0]
	v_pk_add_f32 v[196:197], v[196:197], v[182:183] op_sel_hi:[1,0]
	v_pk_add_f32 v[218:219], v[218:219], v[182:183] op_sel_hi:[1,0]
	v_pk_add_f32 v[220:221], v[220:221], v[182:183] op_sel_hi:[1,0]
	v_pk_add_f32 v[222:223], v[222:223], v[182:183] op_sel_hi:[1,0]
	v_rcp_f32_e32 v188, v188
	v_rcp_f32_e32 v189, v189
	v_rcp_f32_e32 v190, v190
	v_rcp_f32_e32 v191, v191
	v_rcp_f32_e32 v192, v192
	v_rcp_f32_e32 v193, v193
	v_rcp_f32_e32 v194, v194
	v_rcp_f32_e32 v195, v195
	v_rcp_f32_e32 v196, v196
	v_rcp_f32_e32 v197, v197
	v_rcp_f32_e32 v218, v218
	v_rcp_f32_e32 v219, v219
	v_rcp_f32_e32 v220, v220
	v_rcp_f32_e32 v221, v221
	v_rcp_f32_e32 v222, v222
	v_rcp_f32_e32 v223, v223
	v_pk_mul_f32 v[188:189], v[146:147], v[188:189]
	v_pk_mul_f32 v[190:191], v[148:149], v[190:191]
	v_pk_mul_f32 v[192:193], v[150:151], v[192:193]
	v_pk_mul_f32 v[194:195], v[152:153], v[194:195]
	v_pk_mul_f32 v[196:197], v[154:155], v[196:197]
	v_pk_mul_f32 v[218:219], v[156:157], v[218:219]
	v_pk_mul_f32 v[220:221], v[158:159], v[220:221]
	v_pk_mul_f32 v[222:223], v[160:161], v[222:223]
	v_pk_mul_f32 v[188:189], v[188:189], v[130:131]
	v_pk_mul_f32 v[190:191], v[190:191], v[132:133]
	v_pk_mul_f32 v[192:193], v[192:193], v[134:135]
	v_pk_mul_f32 v[194:195], v[194:195], v[136:137]
	v_pk_mul_f32 v[196:197], v[196:197], v[138:139]
	v_pk_mul_f32 v[218:219], v[218:219], v[140:141]
	v_pk_mul_f32 v[220:221], v[220:221], v[142:143]
	v_pk_mul_f32 v[222:223], v[222:223], v[144:145]
	v_cvt_pk_bf16_f32 v188, v188, v189
	v_cvt_pk_bf16_f32 v190, v190, v191
	v_cvt_pk_bf16_f32 v192, v192, v193
	v_cvt_pk_bf16_f32 v194, v194, v195
	v_cvt_pk_bf16_f32 v196, v196, v197
	v_cvt_pk_bf16_f32 v218, v218, v219
	v_cvt_pk_bf16_f32 v220, v220, v221
	v_cvt_pk_bf16_f32 v222, v222, v223
	ds_write_b16 v224, v188 offset:7680
	ds_write_b16_d16_hi v224, v188 offset:7760
	ds_write_b16 v224, v190 offset:7840
	ds_write_b16_d16_hi v224, v190 offset:7920
	ds_write_b16 v224, v192 offset:8320
	ds_write_b16_d16_hi v224, v192 offset:8400
	ds_write_b16 v224, v194 offset:8480
	ds_write_b16_d16_hi v224, v194 offset:8560
	ds_write_b16 v224, v196 offset:8960
	ds_write_b16_d16_hi v224, v196 offset:9040
	ds_write_b16 v224, v218 offset:9120
	ds_write_b16_d16_hi v224, v218 offset:9200
	ds_write_b16 v224, v220 offset:9600
	ds_write_b16_d16_hi v224, v220 offset:9680
	ds_write_b16 v224, v222 offset:9760
	ds_write_b16_d16_hi v224, v222 offset:9840
	s_branch .Lupe_done
; DI unsigned pack2(float a, float b) { f2 v = {a, b}; bf2 r = __builtin_convertvector(v, bf2); return __builtin_bit_cast(unsigned, r); }
; DI int crow(int i, int h) { return (i & 3) + 8 * (i >> 2) + 4 * h; }
;   DI void operator()(f32x16 (&acc)[2][4], int wm, int wn, int r, int h) {
;     ...
; #pragma unroll
;     for (int ig = 0; ig < 4; ++ig)
; #pragma unroll
;       for (int qp = 0; qp < 2; ++qp) {
;         const int i0 = ig * 4 + qp * 2;
;         float u[2][4][2];
; #pragma unroll
;         for (int nb = 0; nb < 2; ++nb) {
;           int xp[4];
; #pragma unroll
;           for (int mb = 0; mb < 4; ++mb) xp[mb] = (int)pack2(acc[nb][mb][i0], acc[nb][mb][i0 + 1]);
;           const float eo0 = ob[nb * 32 + crow(i0, h)], eo1 = ob[nb * 32 + crow(i0 + 1, h)];
;           float w0[2], w1[2], w2[2], bz[2];
;           {
;             const int ff = nt * 128 + wn * 32 + crow(i0, h) + nb * DFF;
;             const f32x2n a0 = *(const f32x2n*)(cw + ff), a1 = *(const f32x2n*)(cw + 2 * DFF + ff), a2 = *(const f32x2n*)(cw + 4 * DFF + ff),
;                          a3 = *(const f32x2n*)(cb + ff);
;             w0[0] = a0.x; w0[1] = a0.y; w1[0] = a1.x; w1[1] = a1.y; w2[0] = a2.x; w2[1] = a2.y; bz[0] = a3.x; bz[1] = a3.y;
;           }
;           int spm = 0;
; #pragma unroll
;           for (int mb = 0; mb < 4; ++mb) {
;             const int spc = __builtin_amdgcn_ds_bpermute(sp << 2, xp[mb]);
;             const int snc = __builtin_amdgcn_ds_bpermute(sn << 2, xp[mb]);
;             const int snn = (mb < 3) ? __builtin_amdgcn_ds_bpermute(sn << 2, xp[mb < 3 ? mb + 1 : 3]) : 0;
;             const int pv = (mb > 0) ? ((r == 0) ? spm : spc) : spc;
;             const int nv = (mb < 3) ? ((r == 31) ? snn : snc) : snc;
;             float prev0 = __int_as_float(pv << 16), prev1 = __int_as_float(pv & 0xffff0000);
;             float next0 = __int_as_float(nv << 16), next1 = __int_as_float(nv & 0xffff0000);
;             if (mb == 0 && r == 0) { prev0 = eo0; prev1 = eo1; }
;             if (mb == 3 && r == 31) { next0 = eo0; next1 = eo1; }
;             spm = spc;
;             prev0 *= pm[mb]; prev1 *= pm[mb];
;             next0 *= nm[mb]; next1 *= nm[mb];
;             u[nb][mb][0] = w0[0] * prev0 + w1[0] * acc[nb][mb][i0] + w2[0] * next0 + bz[0];
;             u[nb][mb][1] = w0[1] * prev1 + w1[1] * acc[nb][mb][i0 + 1] + w2[1] * next1 + bz[1];
;           }
;         }
.Lupe_slow:
	v_mov_b32_e32 v184, v50
	v_mov_b32_e32 v185, v82
	v_pk_fma_f32 v[130:131], v[98:99], v[170:171], v[172:173] op_sel_hi:[1,0,0]
	v_pk_fma_f32 v[132:133], v[100:101], v[170:171], v[172:173] op_sel_hi:[1,0,0]
	v_pk_fma_f32 v[134:135], v[102:103], v[170:171], v[172:173] op_sel_hi:[1,0,0]
	v_pk_fma_f32 v[136:137], v[104:105], v[170:171], v[172:173] op_sel_hi:[1,0,0]
	v_pk_fma_f32 v[138:139], v[106:107], v[170:171], v[172:173] op_sel_hi:[1,0,0]
	v_pk_fma_f32 v[140:141], v[108:109], v[170:171], v[172:173] op_sel_hi:[1,0,0]
	v_pk_fma_f32 v[142:143], v[110:111], v[170:171], v[172:173] op_sel_hi:[1,0,0]
	v_pk_fma_f32 v[144:145], v[112:113], v[170:171], v[172:173] op_sel_hi:[1,0,0]
	v_pk_fma_f32 v[146:147], v[114:115], v[174:175], v[176:177] op_sel_hi:[1,0,0]
	v_pk_fma_f32 v[148:149], v[116:117], v[174:175], v[176:177] op_sel_hi:[1,0,0]
	v_pk_fma_f32 v[150:151], v[118:119], v[174:175], v[176:177] op_sel_hi:[1,0,0]
	v_pk_fma_f32 v[152:153], v[120:121], v[174:175], v[176:177] op_sel_hi:[1,0,0]
	v_pk_fma_f32 v[154:155], v[122:123], v[174:175], v[176:177] op_sel_hi:[1,0,0]
	v_pk_fma_f32 v[156:157], v[124:125], v[174:175], v[176:177] op_sel_hi:[1,0,0]
	v_pk_fma_f32 v[158:159], v[126:127], v[174:175], v[176:177] op_sel_hi:[1,0,0]
	v_pk_fma_f32 v[160:161], v[128:129], v[174:175], v[176:177] op_sel_hi:[1,0,0]
	s_cmp_eq_u32 s36, 0
	s_cselect_b64 exec, s[38:39], -1
	v_fmac_f32_e32 v131, v171, v98
	v_fmac_f32_e32 v130, v173, v99
	v_fmac_f32_e32 v147, v175, v114
	v_fmac_f32_e32 v146, v177, v115
	s_cmp_eq_u32 s36, 1
	s_cselect_b64 exec, s[38:39], -1
	v_fmac_f32_e32 v133, v171, v100
	v_fmac_f32_e32 v132, v173, v101
	v_fmac_f32_e32 v149, v175, v116
	v_fmac_f32_e32 v148, v177, v117
	s_cmp_eq_u32 s36, 2
	s_cselect_b64 exec, s[38:39], -1
	v_fmac_f32_e32 v135, v171, v102
	v_fmac_f32_e32 v134, v173, v103
	v_fmac_f32_e32 v151, v175, v118
	v_fmac_f32_e32 v150, v177, v119
	s_cmp_eq_u32 s36, 3
	s_cselect_b64 exec, s[38:39], -1
	v_fmac_f32_e32 v137, v171, v104
	v_fmac_f32_e32 v136, v173, v105
	v_fmac_f32_e32 v153, v175, v120
	v_fmac_f32_e32 v152, v177, v121
	s_cmp_eq_u32 s36, 4
	s_cselect_b64 exec, s[38:39], -1
	v_fmac_f32_e32 v139, v171, v106
	v_fmac_f32_e32 v138, v173, v107
	v_fmac_f32_e32 v155, v175, v122
	v_fmac_f32_e32 v154, v177, v123
	s_cmp_eq_u32 s36, 5
	s_cselect_b64 exec, s[38:39], -1
	v_fmac_f32_e32 v141, v171, v108
	v_fmac_f32_e32 v140, v173, v109
	v_fmac_f32_e32 v157, v175, v124
	v_fmac_f32_e32 v156, v177, v125
	s_cmp_eq_u32 s36, 6
	s_cselect_b64 exec, s[38:39], -1
	v_fmac_f32_e32 v143, v171, v110
	v_fmac_f32_e32 v142, v173, v111
	v_fmac_f32_e32 v159, v175, v126
	v_fmac_f32_e32 v158, v177, v127
	s_cmp_eq_u32 s36, 7
	s_cselect_b64 exec, s[38:39], -1
	v_fmac_f32_e32 v145, v171, v112
	v_fmac_f32_e32 v144, v173, v113
	v_fmac_f32_e32 v161, v175, v128
	v_fmac_f32_e32 v160, v177, v129
	s_mov_b64 exec, -1
	s_nop 1
	v_permlane32_swap_b32_e32 v98, v101
	v_permlane32_swap_b32_e32 v102, v105
	v_permlane32_swap_b32_e32 v106, v109
	v_permlane32_swap_b32_e32 v110, v113
	v_permlane32_swap_b32_e32 v114, v117
	v_permlane32_swap_b32_e32 v118, v121
	v_permlane32_swap_b32_e32 v122, v125
	v_permlane32_swap_b32_e32 v126, v129
	v_permlane32_swap_b32_e32 v101, v102
	v_permlane32_swap_b32_e32 v105, v106
	v_permlane32_swap_b32_e32 v109, v110
	v_permlane32_swap_b32_e32 v117, v118
	v_permlane32_swap_b32_e32 v121, v122
	v_permlane32_swap_b32_e32 v125, v126
	v_permlane32_swap_b32_e32 v113, v184
	v_permlane32_swap_b32_e32 v129, v185
	s_mov_b32 exec_hi, 0
	ds_read_b32 v98, v226 offset:256
	ds_read_b32 v114, v226 offset:384
	s_mov_b64 exec, -1
	v_fmac_f32_e32 v131, v173, v100
	v_fmac_f32_e32 v132, v171, v99
	v_fmac_f32_e32 v135, v173, v104
	v_fmac_f32_e32 v136, v171, v103
	v_fmac_f32_e32 v139, v173, v108
	v_fmac_f32_e32 v140, v171, v107
	v_fmac_f32_e32 v143, v173, v112
	v_fmac_f32_e32 v144, v171, v111
	v_fmac_f32_e32 v147, v177, v116
	v_fmac_f32_e32 v148, v175, v115
	v_fmac_f32_e32 v151, v177, v120
	v_fmac_f32_e32 v152, v175, v119
	v_fmac_f32_e32 v155, v177, v124
	v_fmac_f32_e32 v156, v175, v123
	v_fmac_f32_e32 v159, v177, v128
	v_fmac_f32_e32 v160, v175, v127
	s_waitcnt lgkmcnt(0)
	v_fmac_f32_e32 v130, v171, v98
	v_fmac_f32_e32 v133, v173, v101
	v_fmac_f32_e32 v134, v171, v102
	v_fmac_f32_e32 v137, v173, v105
	v_fmac_f32_e32 v138, v171, v106
	v_fmac_f32_e32 v141, v173, v109
	v_fmac_f32_e32 v142, v171, v110
	v_fmac_f32_e32 v145, v173, v113
	v_fmac_f32_e32 v146, v175, v114
	v_fmac_f32_e32 v149, v177, v117
	v_fmac_f32_e32 v150, v175, v118
	v_fmac_f32_e32 v153, v177, v121
	v_fmac_f32_e32 v154, v175, v122
	v_fmac_f32_e32 v157, v177, v125
	v_fmac_f32_e32 v158, v175, v126
	v_fmac_f32_e32 v161, v177, v129
	v_pk_mul_f32 v[188:189], v[146:147], v[146:147]
	v_pk_mul_f32 v[190:191], v[148:149], v[148:149]
	v_pk_mul_f32 v[192:193], v[150:151], v[150:151]
	v_pk_mul_f32 v[194:195], v[152:153], v[152:153]
	v_pk_mul_f32 v[196:197], v[154:155], v[154:155]
	v_pk_mul_f32 v[218:219], v[156:157], v[156:157]
	v_pk_mul_f32 v[220:221], v[158:159], v[158:159]
	v_pk_mul_f32 v[222:223], v[160:161], v[160:161]
	v_pk_fma_f32 v[188:189], v[188:189], v[178:179], v[180:181] op_sel_hi:[1,0,0]
	v_pk_fma_f32 v[190:191], v[190:191], v[178:179], v[180:181] op_sel_hi:[1,0,0]
	v_pk_fma_f32 v[192:193], v[192:193], v[178:179], v[180:181] op_sel_hi:[1,0,0]
	v_pk_fma_f32 v[194:195], v[194:195], v[178:179], v[180:181] op_sel_hi:[1,0,0]
	v_pk_fma_f32 v[196:197], v[196:197], v[178:179], v[180:181] op_sel_hi:[1,0,0]
	v_pk_fma_f32 v[218:219], v[218:219], v[178:179], v[180:181] op_sel_hi:[1,0,0]
	v_pk_fma_f32 v[220:221], v[220:221], v[178:179], v[180:181] op_sel_hi:[1,0,0]
	v_pk_fma_f32 v[222:223], v[222:223], v[178:179], v[180:181] op_sel_hi:[1,0,0]
; DI int crow(int i, int h) { return (i & 3) + 8 * (i >> 2) + 4 * h; }
;   DI void operator()(f32x16 (&acc)[2][4], int wm, int wn, int r, int h) {
;     ...
; #pragma unroll
;     for (int ig = 0; ig < 4; ++ig)
; #pragma unroll
;       for (int qp = 0; qp < 2; ++qp) {
;         const int i0 = ig * 4 + qp * 2;
;         float u[2][4][2];
; #pragma unroll
;         for (int nb = 0; nb < 2; ++nb) {
;           int xp[4];
; #pragma unroll
;           for (int mb = 0; mb < 4; ++mb) xp[mb] = (int)pack2(acc[nb][mb][i0], acc[nb][mb][i0 + 1]);
;           const float eo0 = ob[nb * 32 + crow(i0, h)], eo1 = ob[nb * 32 + crow(i0 + 1, h)];
;           float w0[2], w1[2], w2[2], bz[2];
;           {
;             const int ff = nt * 128 + wn * 32 + crow(i0, h) + nb * DFF;
;             const f32x2n a0 = *(const f32x2n*)(cw + ff), a1 = *(const f32x2n*)(cw + 2 * DFF + ff), a2 = *(const f32x2n*)(cw + 4 * DFF + ff),
;                          a3 = *(const f32x2n*)(cb + ff);
;             w0[0] = a0.x; w0[1] = a0.y; w1[0] = a1.x; w1[1] = a1.y; w2[0] = a2.x; w2[1] = a2.y; bz[0] = a3.x; bz[1] = a3.y;
;           }
;           int spm = 0;
; #pragma unroll
;           for (int mb = 0; mb < 4; ++mb) {
;             const int spc = __builtin_amdgcn_ds_bpermute(sp << 2, xp[mb]);
;             const int snc = __builtin_amdgcn_ds_bpermute(sn << 2, xp[mb]);
;             const int snn = (mb < 3) ? __builtin_amdgcn_ds_bpermute(sn << 2, xp[mb < 3 ? mb + 1 : 3]) : 0;
;             const int pv = (mb > 0) ? ((r == 0) ? spm : spc) : spc;
;             const int nv = (mb < 3) ? ((r == 31) ? snn : snc) : snc;
;             float prev0 = __int_as_float(pv << 16), prev1 = __int_as_float(pv & 0xffff0000);
;             float next0 = __int_as_float(nv << 16), next1 = __int_as_float(nv & 0xffff0000);
;             if (mb == 0 && r == 0) { prev0 = eo0; prev1 = eo1; }
;             if (mb == 3 && r == 31) { next0 = eo0; next1 = eo1; }
;             spm = spc;
;             prev0 *= pm[mb]; prev1 *= pm[mb];
;             next0 *= nm[mb]; next1 *= nm[mb];
;             u[nb][mb][0] = w0[0] * prev0 + w1[0] * acc[nb][mb][i0] + w2[0] * next0 + bz[0];
;             u[nb][mb][1] = w0[1] * prev1 + w1[1] * acc[nb][mb][i0 + 1] + w2[1] * next1 + bz[1];
;           }
;         }
; #pragma unroll
;         for (int mb = 0; mb < 4; ++mb)
;           *(unsigned*)(ost + (mb * 32 + r) * 40 + ig * 8 + h * 4 + qp * 2) =
	v_pk_mul_f32 v[188:189], v[146:147], v[188:189]
	v_pk_mul_f32 v[190:191], v[148:149], v[190:191]
	v_pk_mul_f32 v[192:193], v[150:151], v[192:193]
	v_pk_mul_f32 v[194:195], v[152:153], v[194:195]
	v_pk_mul_f32 v[196:197], v[154:155], v[196:197]
	v_pk_mul_f32 v[218:219], v[156:157], v[218:219]
	v_pk_mul_f32 v[220:221], v[158:159], v[220:221]
	v_pk_mul_f32 v[222:223], v[160:161], v[222:223]
	v_exp_f32_e32 v188, v188
	v_exp_f32_e32 v189, v189
	v_exp_f32_e32 v190, v190
	v_exp_f32_e32 v191, v191
	v_exp_f32_e32 v192, v192
	v_exp_f32_e32 v193, v193
	v_exp_f32_e32 v194, v194
	v_exp_f32_e32 v195, v195
	v_exp_f32_e32 v196, v196
	v_exp_f32_e32 v197, v197
	v_exp_f32_e32 v218, v218
	v_exp_f32_e32 v219, v219
	v_exp_f32_e32 v220, v220
	v_exp_f32_e32 v221, v221
	v_exp_f32_e32 v222, v222
	v_exp_f32_e32 v223, v223
	v_pk_add_f32 v[188:189], v[188:189], v[182:183] op_sel_hi:[1,0]
	v_pk_add_f32 v[190:191], v[190:191], v[182:183] op_sel_hi:[1,0]
	v_pk_add_f32 v[192:193], v[192:193], v[182:183] op_sel_hi:[1,0]
	v_pk_add_f32 v[194:195], v[194:195], v[182:183] op_sel_hi:[1,0]
	v_pk_add_f32 v[196:197], v[196:197], v[182:183] op_sel_hi:[1,0]
	v_pk_add_f32 v[218:219], v[218:219], v[182:183] op_sel_hi:[1,0]
	v_pk_add_f32 v[220:221], v[220:221], v[182:183] op_sel_hi:[1,0]
	v_pk_add_f32 v[222:223], v[222:223], v[182:183] op_sel_hi:[1,0]
	v_rcp_f32_e32 v188, v188
	v_rcp_f32_e32 v189, v189
	v_rcp_f32_e32 v190, v190
	v_rcp_f32_e32 v191, v191
	v_rcp_f32_e32 v192, v192
	v_rcp_f32_e32 v193, v193
	v_rcp_f32_e32 v194, v194
	v_rcp_f32_e32 v195, v195
	v_rcp_f32_e32 v196, v196
	v_rcp_f32_e32 v197, v197
	v_rcp_f32_e32 v218, v218
	v_rcp_f32_e32 v219, v219
	v_rcp_f32_e32 v220, v220
	v_rcp_f32_e32 v221, v221
	v_rcp_f32_e32 v222, v222
	v_rcp_f32_e32 v223, v223
	v_pk_mul_f32 v[188:189], v[146:147], v[188:189]
	v_pk_mul_f32 v[190:191], v[148:149], v[190:191]
	v_pk_mul_f32 v[192:193], v[150:151], v[192:193]
	v_pk_mul_f32 v[194:195], v[152:153], v[194:195]
	v_pk_mul_f32 v[196:197], v[154:155], v[196:197]
	v_pk_mul_f32 v[218:219], v[156:157], v[218:219]
	v_pk_mul_f32 v[220:221], v[158:159], v[220:221]
	v_pk_mul_f32 v[222:223], v[160:161], v[222:223]
	v_pk_mul_f32 v[188:189], v[188:189], v[130:131]
	v_pk_mul_f32 v[190:191], v[190:191], v[132:133]
	v_pk_mul_f32 v[192:193], v[192:193], v[134:135]
	v_pk_mul_f32 v[194:195], v[194:195], v[136:137]
	v_pk_mul_f32 v[196:197], v[196:197], v[138:139]
	v_pk_mul_f32 v[218:219], v[218:219], v[140:141]
	v_pk_mul_f32 v[220:221], v[220:221], v[142:143]
	v_pk_mul_f32 v[222:223], v[222:223], v[144:145]
	v_cvt_pk_bf16_f32 v188, v188, v189
	v_cvt_pk_bf16_f32 v190, v190, v191
	v_cvt_pk_bf16_f32 v192, v192, v193
	v_cvt_pk_bf16_f32 v194, v194, v195
	v_cvt_pk_bf16_f32 v196, v196, v197
	v_cvt_pk_bf16_f32 v218, v218, v219
	v_cvt_pk_bf16_f32 v220, v220, v221
	v_cvt_pk_bf16_f32 v222, v222, v223
	ds_write_b16 v224, v188 offset:0
	ds_write_b16_d16_hi v224, v188 offset:80
	ds_write_b16 v224, v190 offset:160
	ds_write_b16_d16_hi v224, v190 offset:240
	ds_write_b16 v224, v192 offset:640
	ds_write_b16_d16_hi v224, v192 offset:720
	ds_write_b16 v224, v194 offset:800
	ds_write_b16_d16_hi v224, v194 offset:880
	ds_write_b16 v224, v196 offset:1280
	ds_write_b16_d16_hi v224, v196 offset:1360
	ds_write_b16 v224, v218 offset:1440
	ds_write_b16_d16_hi v224, v218 offset:1520
	ds_write_b16 v224, v220 offset:1920
	ds_write_b16_d16_hi v224, v220 offset:2000
	ds_write_b16 v224, v222 offset:2080
	ds_write_b16_d16_hi v224, v222 offset:2160
	v_mov_b32_e32 v186, v18
	v_mov_b32_e32 v187, v66
	v_pk_fma_f32 v[130:131], v[50:51], v[170:171], v[172:173] op_sel_hi:[1,0,0]
	v_pk_fma_f32 v[132:133], v[52:53], v[170:171], v[172:173] op_sel_hi:[1,0,0]
	v_pk_fma_f32 v[134:135], v[54:55], v[170:171], v[172:173] op_sel_hi:[1,0,0]
	v_pk_fma_f32 v[136:137], v[56:57], v[170:171], v[172:173] op_sel_hi:[1,0,0]
	v_pk_fma_f32 v[138:139], v[58:59], v[170:171], v[172:173] op_sel_hi:[1,0,0]
	v_pk_fma_f32 v[140:141], v[60:61], v[170:171], v[172:173] op_sel_hi:[1,0,0]
	v_pk_fma_f32 v[142:143], v[62:63], v[170:171], v[172:173] op_sel_hi:[1,0,0]
	v_pk_fma_f32 v[144:145], v[64:65], v[170:171], v[172:173] op_sel_hi:[1,0,0]
	v_pk_fma_f32 v[146:147], v[82:83], v[174:175], v[176:177] op_sel_hi:[1,0,0]
	v_pk_fma_f32 v[148:149], v[84:85], v[174:175], v[176:177] op_sel_hi:[1,0,0]
	v_pk_fma_f32 v[150:151], v[86:87], v[174:175], v[176:177] op_sel_hi:[1,0,0]
	v_pk_fma_f32 v[152:153], v[88:89], v[174:175], v[176:177] op_sel_hi:[1,0,0]
	v_pk_fma_f32 v[154:155], v[90:91], v[174:175], v[176:177] op_sel_hi:[1,0,0]
	v_pk_fma_f32 v[156:157], v[92:93], v[174:175], v[176:177] op_sel_hi:[1,0,0]
	v_pk_fma_f32 v[158:159], v[94:95], v[174:175], v[176:177] op_sel_hi:[1,0,0]
	v_pk_fma_f32 v[160:161], v[96:97], v[174:175], v[176:177] op_sel_hi:[1,0,0]
	s_cmp_eq_u32 s36, 8
	s_cselect_b64 exec, s[38:39], -1
	v_fmac_f32_e32 v131, v171, v50
	v_fmac_f32_e32 v130, v173, v51
	v_fmac_f32_e32 v147, v175, v82
	v_fmac_f32_e32 v146, v177, v83
	s_cmp_eq_u32 s36, 9
	s_cselect_b64 exec, s[38:39], -1
	v_fmac_f32_e32 v133, v171, v52
	v_fmac_f32_e32 v132, v173, v53
	v_fmac_f32_e32 v149, v175, v84
	v_fmac_f32_e32 v148, v177, v85
	s_cmp_eq_u32 s36, 10
	s_cselect_b64 exec, s[38:39], -1
	v_fmac_f32_e32 v135, v171, v54
	v_fmac_f32_e32 v134, v173, v55
	v_fmac_f32_e32 v151, v175, v86
	v_fmac_f32_e32 v150, v177, v87
	s_cmp_eq_u32 s36, 11
	s_cselect_b64 exec, s[38:39], -1
	v_fmac_f32_e32 v137, v171, v56
	v_fmac_f32_e32 v136, v173, v57
	v_fmac_f32_e32 v153, v175, v88
	v_fmac_f32_e32 v152, v177, v89
	s_cmp_eq_u32 s36, 12
	s_cselect_b64 exec, s[38:39], -1
	v_fmac_f32_e32 v139, v171, v58
	v_fmac_f32_e32 v138, v173, v59
	v_fmac_f32_e32 v155, v175, v90
	v_fmac_f32_e32 v154, v177, v91
; DI int crow(int i, int h) { return (i & 3) + 8 * (i >> 2) + 4 * h; }
;   DI void operator()(f32x16 (&acc)[2][4], int wm, int wn, int r, int h) {
;     ...
; #pragma unroll
;     for (int ig = 0; ig < 4; ++ig)
; #pragma unroll
;       for (int qp = 0; qp < 2; ++qp) {
;         const int i0 = ig * 4 + qp * 2;
;         float u[2][4][2];
; #pragma unroll
;         for (int nb = 0; nb < 2; ++nb) {
;           int xp[4];
; #pragma unroll
;           for (int mb = 0; mb < 4; ++mb) xp[mb] = (int)pack2(acc[nb][mb][i0], acc[nb][mb][i0 + 1]);
;           const float eo0 = ob[nb * 32 + crow(i0, h)], eo1 = ob[nb * 32 + crow(i0 + 1, h)];
;           float w0[2], w1[2], w2[2], bz[2];
;           {
;             const int ff = nt * 128 + wn * 32 + crow(i0, h) + nb * DFF;
;             const f32x2n a0 = *(const f32x2n*)(cw + ff), a1 = *(const f32x2n*)(cw + 2 * DFF + ff), a2 = *(const f32x2n*)(cw + 4 * DFF + ff),
;                          a3 = *(const f32x2n*)(cb + ff);
;             w0[0] = a0.x; w0[1] = a0.y; w1[0] = a1.x; w1[1] = a1.y; w2[0] = a2.x; w2[1] = a2.y; bz[0] = a3.x; bz[1] = a3.y;
;           }
;           int spm = 0;
; #pragma unroll
;           for (int mb = 0; mb < 4; ++mb) {
;             const int spc = __builtin_amdgcn_ds_bpermute(sp << 2, xp[mb]);
;             const int snc = __builtin_amdgcn_ds_bpermute(sn << 2, xp[mb]);
;             const int snn = (mb < 3) ? __builtin_amdgcn_ds_bpermute(sn << 2, xp[mb < 3 ? mb + 1 : 3]) : 0;
;             const int pv = (mb > 0) ? ((r == 0) ? spm : spc) : spc;
;             const int nv = (mb < 3) ? ((r == 31) ? snn : snc) : snc;
;             float prev0 = __int_as_float(pv << 16), prev1 = __int_as_float(pv & 0xffff0000);
;             float next0 = __int_as_float(nv << 16), next1 = __int_as_float(nv & 0xffff0000);
;             if (mb == 0 && r == 0) { prev0 = eo0; prev1 = eo1; }
;             if (mb == 3 && r == 31) { next0 = eo0; next1 = eo1; }
;             spm = spc;
;             prev0 *= pm[mb]; prev1 *= pm[mb];
;             next0 *= nm[mb]; next1 *= nm[mb];
;             u[nb][mb][0] = w0[0] * prev0 + w1[0] * acc[nb][mb][i0] + w2[0] * next0 + bz[0];
;             u[nb][mb][1] = w0[1] * prev1 + w1[1] * acc[nb][mb][i0 + 1] + w2[1] * next1 + bz[1];
;           }
;         }
; #pragma unroll
;         for (int mb = 0; mb < 4; ++mb)
;           *(unsigned*)(ost + (mb * 32 + r) * 40 + ig * 8 + h * 4 + qp * 2) =
	s_cmp_eq_u32 s36, 13
	s_cselect_b64 exec, s[38:39], -1
	v_fmac_f32_e32 v141, v171, v60
	v_fmac_f32_e32 v140, v173, v61
	v_fmac_f32_e32 v157, v175, v92
	v_fmac_f32_e32 v156, v177, v93
	s_cmp_eq_u32 s36, 14
	s_cselect_b64 exec, s[38:39], -1
	v_fmac_f32_e32 v143, v171, v62
	v_fmac_f32_e32 v142, v173, v63
	v_fmac_f32_e32 v159, v175, v94
	v_fmac_f32_e32 v158, v177, v95
	s_cmp_eq_u32 s36, 15
	s_cselect_b64 exec, s[38:39], -1
	v_fmac_f32_e32 v145, v171, v64
	v_fmac_f32_e32 v144, v173, v65
	v_fmac_f32_e32 v161, v175, v96
	v_fmac_f32_e32 v160, v177, v97
	s_mov_b64 exec, -1
	s_nop 1
	v_permlane32_swap_b32_e32 v50, v53
	v_permlane32_swap_b32_e32 v54, v57
	v_permlane32_swap_b32_e32 v58, v61
	v_permlane32_swap_b32_e32 v62, v65
	v_permlane32_swap_b32_e32 v82, v85
	v_permlane32_swap_b32_e32 v86, v89
	v_permlane32_swap_b32_e32 v90, v93
	v_permlane32_swap_b32_e32 v94, v97
	v_permlane32_swap_b32_e32 v53, v54
	v_permlane32_swap_b32_e32 v57, v58
	v_permlane32_swap_b32_e32 v61, v62
	v_permlane32_swap_b32_e32 v85, v86
	v_permlane32_swap_b32_e32 v89, v90
	v_permlane32_swap_b32_e32 v93, v94
	v_permlane32_swap_b32_e32 v65, v186
	v_permlane32_swap_b32_e32 v97, v187
	s_mov_b32 exec_hi, 0
	v_mov_b32_e32 v50, v184
	v_mov_b32_e32 v82, v185
	s_mov_b64 exec, -1
	v_fmac_f32_e32 v131, v173, v52
	v_fmac_f32_e32 v132, v171, v51
	v_fmac_f32_e32 v135, v173, v56
	v_fmac_f32_e32 v136, v171, v55
	v_fmac_f32_e32 v139, v173, v60
	v_fmac_f32_e32 v140, v171, v59
	v_fmac_f32_e32 v143, v173, v64
	v_fmac_f32_e32 v144, v171, v63
	v_fmac_f32_e32 v147, v177, v84
	v_fmac_f32_e32 v148, v175, v83
	v_fmac_f32_e32 v151, v177, v88
	v_fmac_f32_e32 v152, v175, v87
	v_fmac_f32_e32 v155, v177, v92
	v_fmac_f32_e32 v156, v175, v91
	v_fmac_f32_e32 v159, v177, v96
	v_fmac_f32_e32 v160, v175, v95
	v_fmac_f32_e32 v130, v171, v50
	v_fmac_f32_e32 v133, v173, v53
	v_fmac_f32_e32 v134, v171, v54
	v_fmac_f32_e32 v137, v173, v57
	v_fmac_f32_e32 v138, v171, v58
	v_fmac_f32_e32 v141, v173, v61
	v_fmac_f32_e32 v142, v171, v62
	v_fmac_f32_e32 v145, v173, v65
	v_fmac_f32_e32 v146, v175, v82
	v_fmac_f32_e32 v149, v177, v85
	v_fmac_f32_e32 v150, v175, v86
	v_fmac_f32_e32 v153, v177, v89
	v_fmac_f32_e32 v154, v175, v90
	v_fmac_f32_e32 v157, v177, v93
	v_fmac_f32_e32 v158, v175, v94
	v_fmac_f32_e32 v161, v177, v97
	v_pk_mul_f32 v[188:189], v[146:147], v[146:147]
	v_pk_mul_f32 v[190:191], v[148:149], v[148:149]
	v_pk_mul_f32 v[192:193], v[150:151], v[150:151]
	v_pk_mul_f32 v[194:195], v[152:153], v[152:153]
	v_pk_mul_f32 v[196:197], v[154:155], v[154:155]
	v_pk_mul_f32 v[218:219], v[156:157], v[156:157]
	v_pk_mul_f32 v[220:221], v[158:159], v[158:159]
	v_pk_mul_f32 v[222:223], v[160:161], v[160:161]
	v_pk_fma_f32 v[188:189], v[188:189], v[178:179], v[180:181] op_sel_hi:[1,0,0]
	v_pk_fma_f32 v[190:191], v[190:191], v[178:179], v[180:181] op_sel_hi:[1,0,0]
	v_pk_fma_f32 v[192:193], v[192:193], v[178:179], v[180:181] op_sel_hi:[1,0,0]
	v_pk_fma_f32 v[194:195], v[194:195], v[178:179], v[180:181] op_sel_hi:[1,0,0]
	v_pk_fma_f32 v[196:197], v[196:197], v[178:179], v[180:181] op_sel_hi:[1,0,0]
	v_pk_fma_f32 v[218:219], v[218:219], v[178:179], v[180:181] op_sel_hi:[1,0,0]
	v_pk_fma_f32 v[220:221], v[220:221], v[178:179], v[180:181] op_sel_hi:[1,0,0]
	v_pk_fma_f32 v[222:223], v[222:223], v[178:179], v[180:181] op_sel_hi:[1,0,0]
	v_pk_mul_f32 v[188:189], v[146:147], v[188:189]
	v_pk_mul_f32 v[190:191], v[148:149], v[190:191]
	v_pk_mul_f32 v[192:193], v[150:151], v[192:193]
	v_pk_mul_f32 v[194:195], v[152:153], v[194:195]
	v_pk_mul_f32 v[196:197], v[154:155], v[196:197]
	v_pk_mul_f32 v[218:219], v[156:157], v[218:219]
	v_pk_mul_f32 v[220:221], v[158:159], v[220:221]
	v_pk_mul_f32 v[222:223], v[160:161], v[222:223]
	v_exp_f32_e32 v188, v188
	v_exp_f32_e32 v189, v189
	v_exp_f32_e32 v190, v190
	v_exp_f32_e32 v191, v191
	v_exp_f32_e32 v192, v192
	v_exp_f32_e32 v193, v193
	v_exp_f32_e32 v194, v194
	v_exp_f32_e32 v195, v195
	v_exp_f32_e32 v196, v196
	v_exp_f32_e32 v197, v197
	v_exp_f32_e32 v218, v218
	v_exp_f32_e32 v219, v219
	v_exp_f32_e32 v220, v220
	v_exp_f32_e32 v221, v221
	v_exp_f32_e32 v222, v222
	v_exp_f32_e32 v223, v223
	v_pk_add_f32 v[188:189], v[188:189], v[182:183] op_sel_hi:[1,0]
	v_pk_add_f32 v[190:191], v[190:191], v[182:183] op_sel_hi:[1,0]
	v_pk_add_f32 v[192:193], v[192:193], v[182:183] op_sel_hi:[1,0]
	v_pk_add_f32 v[194:195], v[194:195], v[182:183] op_sel_hi:[1,0]
	v_pk_add_f32 v[196:197], v[196:197], v[182:183] op_sel_hi:[1,0]
	v_pk_add_f32 v[218:219], v[218:219], v[182:183] op_sel_hi:[1,0]
	v_pk_add_f32 v[220:221], v[220:221], v[182:183] op_sel_hi:[1,0]
	v_pk_add_f32 v[222:223], v[222:223], v[182:183] op_sel_hi:[1,0]
	v_rcp_f32_e32 v188, v188
	v_rcp_f32_e32 v189, v189
	v_rcp_f32_e32 v190, v190
	v_rcp_f32_e32 v191, v191
	v_rcp_f32_e32 v192, v192
	v_rcp_f32_e32 v193, v193
	v_rcp_f32_e32 v194, v194
	v_rcp_f32_e32 v195, v195
	v_rcp_f32_e32 v196, v196
	v_rcp_f32_e32 v197, v197
	v_rcp_f32_e32 v218, v218
	v_rcp_f32_e32 v219, v219
	v_rcp_f32_e32 v220, v220
	v_rcp_f32_e32 v221, v221
	v_rcp_f32_e32 v222, v222
	v_rcp_f32_e32 v223, v223
	v_pk_mul_f32 v[188:189], v[146:147], v[188:189]
	v_pk_mul_f32 v[190:191], v[148:149], v[190:191]
	v_pk_mul_f32 v[192:193], v[150:151], v[192:193]
	v_pk_mul_f32 v[194:195], v[152:153], v[194:195]
	v_pk_mul_f32 v[196:197], v[154:155], v[196:197]
	v_pk_mul_f32 v[218:219], v[156:157], v[218:219]
	v_pk_mul_f32 v[220:221], v[158:159], v[220:221]
	v_pk_mul_f32 v[222:223], v[160:161], v[222:223]
	v_pk_mul_f32 v[188:189], v[188:189], v[130:131]
	v_pk_mul_f32 v[190:191], v[190:191], v[132:133]
	v_pk_mul_f32 v[192:193], v[192:193], v[134:135]
	v_pk_mul_f32 v[194:195], v[194:195], v[136:137]
; DI int crow(int i, int h) { return (i & 3) + 8 * (i >> 2) + 4 * h; }
;   DI void operator()(f32x16 (&acc)[2][4], int wm, int wn, int r, int h) {
;     ...
; #pragma unroll
;     for (int ig = 0; ig < 4; ++ig)
; #pragma unroll
;       for (int qp = 0; qp < 2; ++qp) {
;         const int i0 = ig * 4 + qp * 2;
;         float u[2][4][2];
; #pragma unroll
;         for (int nb = 0; nb < 2; ++nb) {
;           int xp[4];
; #pragma unroll
;           for (int mb = 0; mb < 4; ++mb) xp[mb] = (int)pack2(acc[nb][mb][i0], acc[nb][mb][i0 + 1]);
;           const float eo0 = ob[nb * 32 + crow(i0, h)], eo1 = ob[nb * 32 + crow(i0 + 1, h)];
;           float w0[2], w1[2], w2[2], bz[2];
;           {
;             const int ff = nt * 128 + wn * 32 + crow(i0, h) + nb * DFF;
;             const f32x2n a0 = *(const f32x2n*)(cw + ff), a1 = *(const f32x2n*)(cw + 2 * DFF + ff), a2 = *(const f32x2n*)(cw + 4 * DFF + ff),
;                          a3 = *(const f32x2n*)(cb + ff);
;             w0[0] = a0.x; w0[1] = a0.y; w1[0] = a1.x; w1[1] = a1.y; w2[0] = a2.x; w2[1] = a2.y; bz[0] = a3.x; bz[1] = a3.y;
;           }
;           int spm = 0;
; #pragma unroll
;           for (int mb = 0; mb < 4; ++mb) {
;             const int spc = __builtin_amdgcn_ds_bpermute(sp << 2, xp[mb]);
;             const int snc = __builtin_amdgcn_ds_bpermute(sn << 2, xp[mb]);
;             const int snn = (mb < 3) ? __builtin_amdgcn_ds_bpermute(sn << 2, xp[mb < 3 ? mb + 1 : 3]) : 0;
;             const int pv = (mb > 0) ? ((r == 0) ? spm : spc) : spc;
;             const int nv = (mb < 3) ? ((r == 31) ? snn : snc) : snc;
;             float prev0 = __int_as_float(pv << 16), prev1 = __int_as_float(pv & 0xffff0000);
;             float next0 = __int_as_float(nv << 16), next1 = __int_as_float(nv & 0xffff0000);
;             if (mb == 0 && r == 0) { prev0 = eo0; prev1 = eo1; }
;             if (mb == 3 && r == 31) { next0 = eo0; next1 = eo1; }
;             spm = spc;
;             prev0 *= pm[mb]; prev1 *= pm[mb];
;             next0 *= nm[mb]; next1 *= nm[mb];
;             u[nb][mb][0] = w0[0] * prev0 + w1[0] * acc[nb][mb][i0] + w2[0] * next0 + bz[0];
;             u[nb][mb][1] = w0[1] * prev1 + w1[1] * acc[nb][mb][i0 + 1] + w2[1] * next1 + bz[1];
;           }
;         }
; #pragma unroll
;         for (int mb = 0; mb < 4; ++mb)
;           *(unsigned*)(ost + (mb * 32 + r) * 40 + ig * 8 + h * 4 + qp * 2) =
	v_pk_mul_f32 v[196:197], v[196:197], v[138:139]
	v_pk_mul_f32 v[218:219], v[218:219], v[140:141]
	v_pk_mul_f32 v[220:221], v[220:221], v[142:143]
	v_pk_mul_f32 v[222:223], v[222:223], v[144:145]
	v_cvt_pk_bf16_f32 v188, v188, v189
	v_cvt_pk_bf16_f32 v190, v190, v191
	v_cvt_pk_bf16_f32 v192, v192, v193
	v_cvt_pk_bf16_f32 v194, v194, v195
	v_cvt_pk_bf16_f32 v196, v196, v197
	v_cvt_pk_bf16_f32 v218, v218, v219
	v_cvt_pk_bf16_f32 v220, v220, v221
	v_cvt_pk_bf16_f32 v222, v222, v223
	ds_write_b16 v224, v188 offset:2560
	ds_write_b16_d16_hi v224, v188 offset:2640
	ds_write_b16 v224, v190 offset:2720
	ds_write_b16_d16_hi v224, v190 offset:2800
	ds_write_b16 v224, v192 offset:3200
	ds_write_b16_d16_hi v224, v192 offset:3280
	ds_write_b16 v224, v194 offset:3360
	ds_write_b16_d16_hi v224, v194 offset:3440
	ds_write_b16 v224, v196 offset:3840
	ds_write_b16_d16_hi v224, v196 offset:3920
	ds_write_b16 v224, v218 offset:4000
	ds_write_b16_d16_hi v224, v218 offset:4080
	ds_write_b16 v224, v220 offset:4480
	ds_write_b16_d16_hi v224, v220 offset:4560
	ds_write_b16 v224, v222 offset:4640
	ds_write_b16_d16_hi v224, v222 offset:4720
	v_mov_b32_e32 v184, v2
	v_mov_b32_e32 v185, v34
	v_pk_fma_f32 v[130:131], v[18:19], v[170:171], v[172:173] op_sel_hi:[1,0,0]
	v_pk_fma_f32 v[132:133], v[20:21], v[170:171], v[172:173] op_sel_hi:[1,0,0]
	v_pk_fma_f32 v[134:135], v[22:23], v[170:171], v[172:173] op_sel_hi:[1,0,0]
	v_pk_fma_f32 v[136:137], v[24:25], v[170:171], v[172:173] op_sel_hi:[1,0,0]
	v_pk_fma_f32 v[138:139], v[26:27], v[170:171], v[172:173] op_sel_hi:[1,0,0]
	v_pk_fma_f32 v[140:141], v[28:29], v[170:171], v[172:173] op_sel_hi:[1,0,0]
	v_pk_fma_f32 v[142:143], v[30:31], v[170:171], v[172:173] op_sel_hi:[1,0,0]
	v_pk_fma_f32 v[144:145], v[32:33], v[170:171], v[172:173] op_sel_hi:[1,0,0]
	v_pk_fma_f32 v[146:147], v[66:67], v[174:175], v[176:177] op_sel_hi:[1,0,0]
	v_pk_fma_f32 v[148:149], v[68:69], v[174:175], v[176:177] op_sel_hi:[1,0,0]
	v_pk_fma_f32 v[150:151], v[70:71], v[174:175], v[176:177] op_sel_hi:[1,0,0]
	v_pk_fma_f32 v[152:153], v[72:73], v[174:175], v[176:177] op_sel_hi:[1,0,0]
	v_pk_fma_f32 v[154:155], v[74:75], v[174:175], v[176:177] op_sel_hi:[1,0,0]
	v_pk_fma_f32 v[156:157], v[76:77], v[174:175], v[176:177] op_sel_hi:[1,0,0]
	v_pk_fma_f32 v[158:159], v[78:79], v[174:175], v[176:177] op_sel_hi:[1,0,0]
	v_pk_fma_f32 v[160:161], v[80:81], v[174:175], v[176:177] op_sel_hi:[1,0,0]
	s_cmp_eq_u32 s36, 16
	s_cselect_b64 exec, s[38:39], -1
	v_fmac_f32_e32 v131, v171, v18
	v_fmac_f32_e32 v130, v173, v19
	v_fmac_f32_e32 v147, v175, v66
	v_fmac_f32_e32 v146, v177, v67
	s_cmp_eq_u32 s36, 17
	s_cselect_b64 exec, s[38:39], -1
	v_fmac_f32_e32 v133, v171, v20
	v_fmac_f32_e32 v132, v173, v21
	v_fmac_f32_e32 v149, v175, v68
	v_fmac_f32_e32 v148, v177, v69
	s_cmp_eq_u32 s36, 18
	s_cselect_b64 exec, s[38:39], -1
	v_fmac_f32_e32 v135, v171, v22
	v_fmac_f32_e32 v134, v173, v23
	v_fmac_f32_e32 v151, v175, v70
	v_fmac_f32_e32 v150, v177, v71
	s_cmp_eq_u32 s36, 19
	s_cselect_b64 exec, s[38:39], -1
	v_fmac_f32_e32 v137, v171, v24
	v_fmac_f32_e32 v136, v173, v25
	v_fmac_f32_e32 v153, v175, v72
	v_fmac_f32_e32 v152, v177, v73
	s_cmp_eq_u32 s36, 20
	s_cselect_b64 exec, s[38:39], -1
	v_fmac_f32_e32 v139, v171, v26
	v_fmac_f32_e32 v138, v173, v27
	v_fmac_f32_e32 v155, v175, v74
	v_fmac_f32_e32 v154, v177, v75
	s_cmp_eq_u32 s36, 21
	s_cselect_b64 exec, s[38:39], -1
	v_fmac_f32_e32 v141, v171, v28
	v_fmac_f32_e32 v140, v173, v29
	v_fmac_f32_e32 v157, v175, v76
	v_fmac_f32_e32 v156, v177, v77
	s_cmp_eq_u32 s36, 22
	s_cselect_b64 exec, s[38:39], -1
	v_fmac_f32_e32 v143, v171, v30
	v_fmac_f32_e32 v142, v173, v31
	v_fmac_f32_e32 v159, v175, v78
	v_fmac_f32_e32 v158, v177, v79
	s_cmp_eq_u32 s36, 23
	s_cselect_b64 exec, s[38:39], -1
	v_fmac_f32_e32 v145, v171, v32
	v_fmac_f32_e32 v144, v173, v33
	v_fmac_f32_e32 v161, v175, v80
	v_fmac_f32_e32 v160, v177, v81
	s_mov_b64 exec, -1
	s_nop 1
	v_permlane32_swap_b32_e32 v18, v21
	v_permlane32_swap_b32_e32 v22, v25
	v_permlane32_swap_b32_e32 v26, v29
	v_permlane32_swap_b32_e32 v30, v33
	v_permlane32_swap_b32_e32 v66, v69
	v_permlane32_swap_b32_e32 v70, v73
	v_permlane32_swap_b32_e32 v74, v77
	v_permlane32_swap_b32_e32 v78, v81
	v_permlane32_swap_b32_e32 v21, v22
	v_permlane32_swap_b32_e32 v25, v26
	v_permlane32_swap_b32_e32 v29, v30
	v_permlane32_swap_b32_e32 v69, v70
	v_permlane32_swap_b32_e32 v73, v74
	v_permlane32_swap_b32_e32 v77, v78
	v_permlane32_swap_b32_e32 v33, v184
	v_permlane32_swap_b32_e32 v81, v185
	s_mov_b32 exec_hi, 0
	v_mov_b32_e32 v18, v186
	v_mov_b32_e32 v66, v187
	s_mov_b64 exec, -1
	v_fmac_f32_e32 v131, v173, v20
	v_fmac_f32_e32 v132, v171, v19
	v_fmac_f32_e32 v135, v173, v24
	v_fmac_f32_e32 v136, v171, v23
	v_fmac_f32_e32 v139, v173, v28
	v_fmac_f32_e32 v140, v171, v27
	v_fmac_f32_e32 v143, v173, v32
	v_fmac_f32_e32 v144, v171, v31
	v_fmac_f32_e32 v147, v177, v68
	v_fmac_f32_e32 v148, v175, v67
	v_fmac_f32_e32 v151, v177, v72
	v_fmac_f32_e32 v152, v175, v71
	v_fmac_f32_e32 v155, v177, v76
	v_fmac_f32_e32 v156, v175, v75
	v_fmac_f32_e32 v159, v177, v80
	v_fmac_f32_e32 v160, v175, v79
	v_fmac_f32_e32 v130, v171, v18
	v_fmac_f32_e32 v133, v173, v21
	v_fmac_f32_e32 v134, v171, v22
	v_fmac_f32_e32 v137, v173, v25
	v_fmac_f32_e32 v138, v171, v26
	v_fmac_f32_e32 v141, v173, v29
	v_fmac_f32_e32 v142, v171, v30
	v_fmac_f32_e32 v145, v173, v33
	v_fmac_f32_e32 v146, v175, v66
	v_fmac_f32_e32 v149, v177, v69
	v_fmac_f32_e32 v150, v175, v70
	v_fmac_f32_e32 v153, v177, v73
	v_fmac_f32_e32 v154, v175, v74
	v_fmac_f32_e32 v157, v177, v77
	v_fmac_f32_e32 v158, v175, v78
	v_fmac_f32_e32 v161, v177, v81
	v_pk_mul_f32 v[188:189], v[146:147], v[146:147]
; DI int crow(int i, int h) { return (i & 3) + 8 * (i >> 2) + 4 * h; }
;   DI void operator()(f32x16 (&acc)[2][4], int wm, int wn, int r, int h) {
;     ...
; #pragma unroll
;     for (int ig = 0; ig < 4; ++ig)
; #pragma unroll
;       for (int qp = 0; qp < 2; ++qp) {
;         const int i0 = ig * 4 + qp * 2;
;         float u[2][4][2];
; #pragma unroll
;         for (int nb = 0; nb < 2; ++nb) {
;           int xp[4];
; #pragma unroll
;           for (int mb = 0; mb < 4; ++mb) xp[mb] = (int)pack2(acc[nb][mb][i0], acc[nb][mb][i0 + 1]);
;           const float eo0 = ob[nb * 32 + crow(i0, h)], eo1 = ob[nb * 32 + crow(i0 + 1, h)];
;           float w0[2], w1[2], w2[2], bz[2];
;           {
;             const int ff = nt * 128 + wn * 32 + crow(i0, h) + nb * DFF;
;             const f32x2n a0 = *(const f32x2n*)(cw + ff), a1 = *(const f32x2n*)(cw + 2 * DFF + ff), a2 = *(const f32x2n*)(cw + 4 * DFF + ff),
;                          a3 = *(const f32x2n*)(cb + ff);
;             w0[0] = a0.x; w0[1] = a0.y; w1[0] = a1.x; w1[1] = a1.y; w2[0] = a2.x; w2[1] = a2.y; bz[0] = a3.x; bz[1] = a3.y;
;           }
;           int spm = 0;
; #pragma unroll
;           for (int mb = 0; mb < 4; ++mb) {
;             const int spc = __builtin_amdgcn_ds_bpermute(sp << 2, xp[mb]);
;             const int snc = __builtin_amdgcn_ds_bpermute(sn << 2, xp[mb]);
;             const int snn = (mb < 3) ? __builtin_amdgcn_ds_bpermute(sn << 2, xp[mb < 3 ? mb + 1 : 3]) : 0;
;             const int pv = (mb > 0) ? ((r == 0) ? spm : spc) : spc;
;             const int nv = (mb < 3) ? ((r == 31) ? snn : snc) : snc;
;             float prev0 = __int_as_float(pv << 16), prev1 = __int_as_float(pv & 0xffff0000);
;             float next0 = __int_as_float(nv << 16), next1 = __int_as_float(nv & 0xffff0000);
;             if (mb == 0 && r == 0) { prev0 = eo0; prev1 = eo1; }
;             if (mb == 3 && r == 31) { next0 = eo0; next1 = eo1; }
;             spm = spc;
;             prev0 *= pm[mb]; prev1 *= pm[mb];
;             next0 *= nm[mb]; next1 *= nm[mb];
;             u[nb][mb][0] = w0[0] * prev0 + w1[0] * acc[nb][mb][i0] + w2[0] * next0 + bz[0];
;             u[nb][mb][1] = w0[1] * prev1 + w1[1] * acc[nb][mb][i0 + 1] + w2[1] * next1 + bz[1];
;           }
;         }
; #pragma unroll
;         for (int mb = 0; mb < 4; ++mb)
;           *(unsigned*)(ost + (mb * 32 + r) * 40 + ig * 8 + h * 4 + qp * 2) =
	v_pk_mul_f32 v[190:191], v[148:149], v[148:149]
	v_pk_mul_f32 v[192:193], v[150:151], v[150:151]
	v_pk_mul_f32 v[194:195], v[152:153], v[152:153]
	v_pk_mul_f32 v[196:197], v[154:155], v[154:155]
	v_pk_mul_f32 v[218:219], v[156:157], v[156:157]
	v_pk_mul_f32 v[220:221], v[158:159], v[158:159]
	v_pk_mul_f32 v[222:223], v[160:161], v[160:161]
	v_pk_fma_f32 v[188:189], v[188:189], v[178:179], v[180:181] op_sel_hi:[1,0,0]
	v_pk_fma_f32 v[190:191], v[190:191], v[178:179], v[180:181] op_sel_hi:[1,0,0]
	v_pk_fma_f32 v[192:193], v[192:193], v[178:179], v[180:181] op_sel_hi:[1,0,0]
	v_pk_fma_f32 v[194:195], v[194:195], v[178:179], v[180:181] op_sel_hi:[1,0,0]
	v_pk_fma_f32 v[196:197], v[196:197], v[178:179], v[180:181] op_sel_hi:[1,0,0]
	v_pk_fma_f32 v[218:219], v[218:219], v[178:179], v[180:181] op_sel_hi:[1,0,0]
	v_pk_fma_f32 v[220:221], v[220:221], v[178:179], v[180:181] op_sel_hi:[1,0,0]
	v_pk_fma_f32 v[222:223], v[222:223], v[178:179], v[180:181] op_sel_hi:[1,0,0]
	v_pk_mul_f32 v[188:189], v[146:147], v[188:189]
	v_pk_mul_f32 v[190:191], v[148:149], v[190:191]
	v_pk_mul_f32 v[192:193], v[150:151], v[192:193]
	v_pk_mul_f32 v[194:195], v[152:153], v[194:195]
	v_pk_mul_f32 v[196:197], v[154:155], v[196:197]
	v_pk_mul_f32 v[218:219], v[156:157], v[218:219]
	v_pk_mul_f32 v[220:221], v[158:159], v[220:221]
	v_pk_mul_f32 v[222:223], v[160:161], v[222:223]
	v_exp_f32_e32 v188, v188
	v_exp_f32_e32 v189, v189
	v_exp_f32_e32 v190, v190
	v_exp_f32_e32 v191, v191
	v_exp_f32_e32 v192, v192
	v_exp_f32_e32 v193, v193
	v_exp_f32_e32 v194, v194
	v_exp_f32_e32 v195, v195
	v_exp_f32_e32 v196, v196
	v_exp_f32_e32 v197, v197
	v_exp_f32_e32 v218, v218
	v_exp_f32_e32 v219, v219
	v_exp_f32_e32 v220, v220
	v_exp_f32_e32 v221, v221
	v_exp_f32_e32 v222, v222
	v_exp_f32_e32 v223, v223
	v_pk_add_f32 v[188:189], v[188:189], v[182:183] op_sel_hi:[1,0]
	v_pk_add_f32 v[190:191], v[190:191], v[182:183] op_sel_hi:[1,0]
	v_pk_add_f32 v[192:193], v[192:193], v[182:183] op_sel_hi:[1,0]
	v_pk_add_f32 v[194:195], v[194:195], v[182:183] op_sel_hi:[1,0]
	v_pk_add_f32 v[196:197], v[196:197], v[182:183] op_sel_hi:[1,0]
	v_pk_add_f32 v[218:219], v[218:219], v[182:183] op_sel_hi:[1,0]
	v_pk_add_f32 v[220:221], v[220:221], v[182:183] op_sel_hi:[1,0]
	v_pk_add_f32 v[222:223], v[222:223], v[182:183] op_sel_hi:[1,0]
	v_rcp_f32_e32 v188, v188
	v_rcp_f32_e32 v189, v189
	v_rcp_f32_e32 v190, v190
	v_rcp_f32_e32 v191, v191
	v_rcp_f32_e32 v192, v192
	v_rcp_f32_e32 v193, v193
	v_rcp_f32_e32 v194, v194
	v_rcp_f32_e32 v195, v195
	v_rcp_f32_e32 v196, v196
	v_rcp_f32_e32 v197, v197
	v_rcp_f32_e32 v218, v218
	v_rcp_f32_e32 v219, v219
	v_rcp_f32_e32 v220, v220
	v_rcp_f32_e32 v221, v221
	v_rcp_f32_e32 v222, v222
	v_rcp_f32_e32 v223, v223
	v_pk_mul_f32 v[188:189], v[146:147], v[188:189]
	v_pk_mul_f32 v[190:191], v[148:149], v[190:191]
	v_pk_mul_f32 v[192:193], v[150:151], v[192:193]
	v_pk_mul_f32 v[194:195], v[152:153], v[194:195]
	v_pk_mul_f32 v[196:197], v[154:155], v[196:197]
	v_pk_mul_f32 v[218:219], v[156:157], v[218:219]
	v_pk_mul_f32 v[220:221], v[158:159], v[220:221]
	v_pk_mul_f32 v[222:223], v[160:161], v[222:223]
	v_pk_mul_f32 v[188:189], v[188:189], v[130:131]
	v_pk_mul_f32 v[190:191], v[190:191], v[132:133]
	v_pk_mul_f32 v[192:193], v[192:193], v[134:135]
	v_pk_mul_f32 v[194:195], v[194:195], v[136:137]
	v_pk_mul_f32 v[196:197], v[196:197], v[138:139]
	v_pk_mul_f32 v[218:219], v[218:219], v[140:141]
	v_pk_mul_f32 v[220:221], v[220:221], v[142:143]
	v_pk_mul_f32 v[222:223], v[222:223], v[144:145]
	v_cvt_pk_bf16_f32 v188, v188, v189
	v_cvt_pk_bf16_f32 v190, v190, v191
	v_cvt_pk_bf16_f32 v192, v192, v193
	v_cvt_pk_bf16_f32 v194, v194, v195
	v_cvt_pk_bf16_f32 v196, v196, v197
	v_cvt_pk_bf16_f32 v218, v218, v219
	v_cvt_pk_bf16_f32 v220, v220, v221
	v_cvt_pk_bf16_f32 v222, v222, v223
	ds_write_b16 v224, v188 offset:5120
	ds_write_b16_d16_hi v224, v188 offset:5200
	ds_write_b16 v224, v190 offset:5280
	ds_write_b16_d16_hi v224, v190 offset:5360
	ds_write_b16 v224, v192 offset:5760
	ds_write_b16_d16_hi v224, v192 offset:5840
	ds_write_b16 v224, v194 offset:5920
	ds_write_b16_d16_hi v224, v194 offset:6000
	ds_write_b16 v224, v196 offset:6400
	ds_write_b16_d16_hi v224, v196 offset:6480
	ds_write_b16 v224, v218 offset:6560
	ds_write_b16_d16_hi v224, v218 offset:6640
	ds_write_b16 v224, v220 offset:7040
	ds_write_b16_d16_hi v224, v220 offset:7120
	ds_write_b16 v224, v222 offset:7200
	ds_write_b16_d16_hi v224, v222 offset:7280
	v_pk_fma_f32 v[130:131], v[2:3], v[170:171], v[172:173] op_sel_hi:[1,0,0]
	v_pk_fma_f32 v[132:133], v[4:5], v[170:171], v[172:173] op_sel_hi:[1,0,0]
	v_pk_fma_f32 v[134:135], v[6:7], v[170:171], v[172:173] op_sel_hi:[1,0,0]
	v_pk_fma_f32 v[136:137], v[8:9], v[170:171], v[172:173] op_sel_hi:[1,0,0]
	v_pk_fma_f32 v[138:139], v[10:11], v[170:171], v[172:173] op_sel_hi:[1,0,0]
	v_pk_fma_f32 v[140:141], v[12:13], v[170:171], v[172:173] op_sel_hi:[1,0,0]
	v_pk_fma_f32 v[142:143], v[14:15], v[170:171], v[172:173] op_sel_hi:[1,0,0]
	v_pk_fma_f32 v[144:145], v[16:17], v[170:171], v[172:173] op_sel_hi:[1,0,0]
	v_pk_fma_f32 v[146:147], v[34:35], v[174:175], v[176:177] op_sel_hi:[1,0,0]
	v_pk_fma_f32 v[148:149], v[36:37], v[174:175], v[176:177] op_sel_hi:[1,0,0]
	v_pk_fma_f32 v[150:151], v[38:39], v[174:175], v[176:177] op_sel_hi:[1,0,0]
	v_pk_fma_f32 v[152:153], v[40:41], v[174:175], v[176:177] op_sel_hi:[1,0,0]
	v_pk_fma_f32 v[154:155], v[42:43], v[174:175], v[176:177] op_sel_hi:[1,0,0]
	v_pk_fma_f32 v[156:157], v[44:45], v[174:175], v[176:177] op_sel_hi:[1,0,0]
	v_pk_fma_f32 v[158:159], v[46:47], v[174:175], v[176:177] op_sel_hi:[1,0,0]
	v_pk_fma_f32 v[160:161], v[48:49], v[174:175], v[176:177] op_sel_hi:[1,0,0]
; DI unsigned pack2(float a, float b) { f2 v = {a, b}; bf2 r = __builtin_convertvector(v, bf2); return __builtin_bit_cast(unsigned, r); }
; DI int crow(int i, int h) { return (i & 3) + 8 * (i >> 2) + 4 * h; }
;   DI void operator()(f32x16 (&acc)[2][4], int wm, int wn, int r, int h) {
;     ...
; #pragma unroll
;     for (int ig = 0; ig < 4; ++ig)
; #pragma unroll
;       for (int qp = 0; qp < 2; ++qp) {
;         const int i0 = ig * 4 + qp * 2;
;         float u[2][4][2];
; #pragma unroll
;         for (int nb = 0; nb < 2; ++nb) {
;           int xp[4];
; #pragma unroll
;           for (int mb = 0; mb < 4; ++mb) xp[mb] = (int)pack2(acc[nb][mb][i0], acc[nb][mb][i0 + 1]);
;           const float eo0 = ob[nb * 32 + crow(i0, h)], eo1 = ob[nb * 32 + crow(i0 + 1, h)];
;           float w0[2], w1[2], w2[2], bz[2];
;           {
;             const int ff = nt * 128 + wn * 32 + crow(i0, h) + nb * DFF;
;             const f32x2n a0 = *(const f32x2n*)(cw + ff), a1 = *(const f32x2n*)(cw + 2 * DFF + ff), a2 = *(const f32x2n*)(cw + 4 * DFF + ff),
;                          a3 = *(const f32x2n*)(cb + ff);
;             w0[0] = a0.x; w0[1] = a0.y; w1[0] = a1.x; w1[1] = a1.y; w2[0] = a2.x; w2[1] = a2.y; bz[0] = a3.x; bz[1] = a3.y;
;           }
;           int spm = 0;
; #pragma unroll
;           for (int mb = 0; mb < 4; ++mb) {
;             const int spc = __builtin_amdgcn_ds_bpermute(sp << 2, xp[mb]);
;             const int snc = __builtin_amdgcn_ds_bpermute(sn << 2, xp[mb]);
;             const int snn = (mb < 3) ? __builtin_amdgcn_ds_bpermute(sn << 2, xp[mb < 3 ? mb + 1 : 3]) : 0;
;             const int pv = (mb > 0) ? ((r == 0) ? spm : spc) : spc;
;             const int nv = (mb < 3) ? ((r == 31) ? snn : snc) : snc;
;             float prev0 = __int_as_float(pv << 16), prev1 = __int_as_float(pv & 0xffff0000);
;             float next0 = __int_as_float(nv << 16), next1 = __int_as_float(nv & 0xffff0000);
;             if (mb == 0 && r == 0) { prev0 = eo0; prev1 = eo1; }
;             if (mb == 3 && r == 31) { next0 = eo0; next1 = eo1; }
;             spm = spc;
;             prev0 *= pm[mb]; prev1 *= pm[mb];
;             next0 *= nm[mb]; next1 *= nm[mb];
;             u[nb][mb][0] = w0[0] * prev0 + w1[0] * acc[nb][mb][i0] + w2[0] * next0 + bz[0];
;             u[nb][mb][1] = w0[1] * prev1 + w1[1] * acc[nb][mb][i0 + 1] + w2[1] * next1 + bz[1];
;           }
;         }
	s_cmp_eq_u32 s36, 24
	s_cselect_b64 exec, s[38:39], -1
	v_fmac_f32_e32 v131, v171, v2
	v_fmac_f32_e32 v130, v173, v3
	v_fmac_f32_e32 v147, v175, v34
	v_fmac_f32_e32 v146, v177, v35
	s_cmp_eq_u32 s36, 25
	s_cselect_b64 exec, s[38:39], -1
	v_fmac_f32_e32 v133, v171, v4
	v_fmac_f32_e32 v132, v173, v5
	v_fmac_f32_e32 v149, v175, v36
	v_fmac_f32_e32 v148, v177, v37
	s_cmp_eq_u32 s36, 26
	s_cselect_b64 exec, s[38:39], -1
	v_fmac_f32_e32 v135, v171, v6
	v_fmac_f32_e32 v134, v173, v7
	v_fmac_f32_e32 v151, v175, v38
	v_fmac_f32_e32 v150, v177, v39
	s_cmp_eq_u32 s36, 27
	s_cselect_b64 exec, s[38:39], -1
	v_fmac_f32_e32 v137, v171, v8
	v_fmac_f32_e32 v136, v173, v9
	v_fmac_f32_e32 v153, v175, v40
	v_fmac_f32_e32 v152, v177, v41
	s_cmp_eq_u32 s36, 28
	s_cselect_b64 exec, s[38:39], -1
	v_fmac_f32_e32 v139, v171, v10
	v_fmac_f32_e32 v138, v173, v11
	v_fmac_f32_e32 v155, v175, v42
	v_fmac_f32_e32 v154, v177, v43
	s_cmp_eq_u32 s36, 29
	s_cselect_b64 exec, s[38:39], -1
	v_fmac_f32_e32 v141, v171, v12
	v_fmac_f32_e32 v140, v173, v13
	v_fmac_f32_e32 v157, v175, v44
	v_fmac_f32_e32 v156, v177, v45
	s_cmp_eq_u32 s36, 30
	s_cselect_b64 exec, s[38:39], -1
	v_fmac_f32_e32 v143, v171, v14
	v_fmac_f32_e32 v142, v173, v15
	v_fmac_f32_e32 v159, v175, v46
	v_fmac_f32_e32 v158, v177, v47
	s_cmp_eq_u32 s36, 31
	s_cselect_b64 exec, s[38:39], -1
	v_fmac_f32_e32 v145, v171, v16
	v_fmac_f32_e32 v144, v173, v17
	v_fmac_f32_e32 v161, v175, v48
	v_fmac_f32_e32 v160, v177, v49
	s_mov_b64 exec, -1
	s_nop 1
	v_permlane32_swap_b32_e32 v2, v5
	v_permlane32_swap_b32_e32 v6, v9
	v_permlane32_swap_b32_e32 v10, v13
	v_permlane32_swap_b32_e32 v14, v17
	v_permlane32_swap_b32_e32 v34, v37
	v_permlane32_swap_b32_e32 v38, v41
	v_permlane32_swap_b32_e32 v42, v45
	v_permlane32_swap_b32_e32 v46, v49
	v_permlane32_swap_b32_e32 v5, v6
	v_permlane32_swap_b32_e32 v9, v10
	v_permlane32_swap_b32_e32 v13, v14
	v_permlane32_swap_b32_e32 v37, v38
	v_permlane32_swap_b32_e32 v41, v42
	v_permlane32_swap_b32_e32 v45, v46
	s_mov_b32 exec_lo, 0
	ds_read_b32 v17, v226 offset:0
	ds_read_b32 v49, v226 offset:128
	s_mov_b64 exec, -1
	s_mov_b32 exec_hi, 0
	v_mov_b32_e32 v2, v184
	v_mov_b32_e32 v34, v185
	s_mov_b64 exec, -1
	v_fmac_f32_e32 v131, v173, v4
	v_fmac_f32_e32 v132, v171, v3
	v_fmac_f32_e32 v135, v173, v8
	v_fmac_f32_e32 v136, v171, v7
	v_fmac_f32_e32 v139, v173, v12
	v_fmac_f32_e32 v140, v171, v11
	v_fmac_f32_e32 v143, v173, v16
	v_fmac_f32_e32 v144, v171, v15
	v_fmac_f32_e32 v147, v177, v36
	v_fmac_f32_e32 v148, v175, v35
	v_fmac_f32_e32 v151, v177, v40
	v_fmac_f32_e32 v152, v175, v39
	v_fmac_f32_e32 v155, v177, v44
	v_fmac_f32_e32 v156, v175, v43
	v_fmac_f32_e32 v159, v177, v48
	v_fmac_f32_e32 v160, v175, v47
	s_waitcnt lgkmcnt(0)
; DI int crow(int i, int h) { return (i & 3) + 8 * (i >> 2) + 4 * h; }
;   DI void operator()(f32x16 (&acc)[2][4], int wm, int wn, int r, int h) {
;     ...
; #pragma unroll
;     for (int ig = 0; ig < 4; ++ig)
; #pragma unroll
;       for (int qp = 0; qp < 2; ++qp) {
;         const int i0 = ig * 4 + qp * 2;
;         float u[2][4][2];
; #pragma unroll
;         for (int nb = 0; nb < 2; ++nb) {
;           int xp[4];
; #pragma unroll
;           for (int mb = 0; mb < 4; ++mb) xp[mb] = (int)pack2(acc[nb][mb][i0], acc[nb][mb][i0 + 1]);
;           const float eo0 = ob[nb * 32 + crow(i0, h)], eo1 = ob[nb * 32 + crow(i0 + 1, h)];
;           float w0[2], w1[2], w2[2], bz[2];
;           {
;             const int ff = nt * 128 + wn * 32 + crow(i0, h) + nb * DFF;
;             const f32x2n a0 = *(const f32x2n*)(cw + ff), a1 = *(const f32x2n*)(cw + 2 * DFF + ff), a2 = *(const f32x2n*)(cw + 4 * DFF + ff),
;                          a3 = *(const f32x2n*)(cb + ff);
;             w0[0] = a0.x; w0[1] = a0.y; w1[0] = a1.x; w1[1] = a1.y; w2[0] = a2.x; w2[1] = a2.y; bz[0] = a3.x; bz[1] = a3.y;
;           }
;           int spm = 0;
; #pragma unroll
;           for (int mb = 0; mb < 4; ++mb) {
;             const int spc = __builtin_amdgcn_ds_bpermute(sp << 2, xp[mb]);
;             const int snc = __builtin_amdgcn_ds_bpermute(sn << 2, xp[mb]);
;             const int snn = (mb < 3) ? __builtin_amdgcn_ds_bpermute(sn << 2, xp[mb < 3 ? mb + 1 : 3]) : 0;
;             const int pv = (mb > 0) ? ((r == 0) ? spm : spc) : spc;
;             const int nv = (mb < 3) ? ((r == 31) ? snn : snc) : snc;
;             float prev0 = __int_as_float(pv << 16), prev1 = __int_as_float(pv & 0xffff0000);
;             float next0 = __int_as_float(nv << 16), next1 = __int_as_float(nv & 0xffff0000);
;             if (mb == 0 && r == 0) { prev0 = eo0; prev1 = eo1; }
;             if (mb == 3 && r == 31) { next0 = eo0; next1 = eo1; }
;             spm = spc;
;             prev0 *= pm[mb]; prev1 *= pm[mb];
;             next0 *= nm[mb]; next1 *= nm[mb];
;             u[nb][mb][0] = w0[0] * prev0 + w1[0] * acc[nb][mb][i0] + w2[0] * next0 + bz[0];
;             u[nb][mb][1] = w0[1] * prev1 + w1[1] * acc[nb][mb][i0 + 1] + w2[1] * next1 + bz[1];
;           }
;         }
; #pragma unroll
;         for (int mb = 0; mb < 4; ++mb)
;           *(unsigned*)(ost + (mb * 32 + r) * 40 + ig * 8 + h * 4 + qp * 2) =
	v_fmac_f32_e32 v130, v171, v2
	v_fmac_f32_e32 v133, v173, v5
	v_fmac_f32_e32 v134, v171, v6
	v_fmac_f32_e32 v137, v173, v9
	v_fmac_f32_e32 v138, v171, v10
	v_fmac_f32_e32 v141, v173, v13
	v_fmac_f32_e32 v142, v171, v14
	v_fmac_f32_e32 v145, v173, v17
	v_fmac_f32_e32 v146, v175, v34
	v_fmac_f32_e32 v149, v177, v37
	v_fmac_f32_e32 v150, v175, v38
	v_fmac_f32_e32 v153, v177, v41
	v_fmac_f32_e32 v154, v175, v42
	v_fmac_f32_e32 v157, v177, v45
	v_fmac_f32_e32 v158, v175, v46
	v_fmac_f32_e32 v161, v177, v49
	v_pk_mul_f32 v[188:189], v[146:147], v[146:147]
	v_pk_mul_f32 v[190:191], v[148:149], v[148:149]
	v_pk_mul_f32 v[192:193], v[150:151], v[150:151]
	v_pk_mul_f32 v[194:195], v[152:153], v[152:153]
	v_pk_mul_f32 v[196:197], v[154:155], v[154:155]
	v_pk_mul_f32 v[218:219], v[156:157], v[156:157]
	v_pk_mul_f32 v[220:221], v[158:159], v[158:159]
	v_pk_mul_f32 v[222:223], v[160:161], v[160:161]
	v_pk_fma_f32 v[188:189], v[188:189], v[178:179], v[180:181] op_sel_hi:[1,0,0]
	v_pk_fma_f32 v[190:191], v[190:191], v[178:179], v[180:181] op_sel_hi:[1,0,0]
	v_pk_fma_f32 v[192:193], v[192:193], v[178:179], v[180:181] op_sel_hi:[1,0,0]
	v_pk_fma_f32 v[194:195], v[194:195], v[178:179], v[180:181] op_sel_hi:[1,0,0]
	v_pk_fma_f32 v[196:197], v[196:197], v[178:179], v[180:181] op_sel_hi:[1,0,0]
	v_pk_fma_f32 v[218:219], v[218:219], v[178:179], v[180:181] op_sel_hi:[1,0,0]
	v_pk_fma_f32 v[220:221], v[220:221], v[178:179], v[180:181] op_sel_hi:[1,0,0]
	v_pk_fma_f32 v[222:223], v[222:223], v[178:179], v[180:181] op_sel_hi:[1,0,0]
	v_pk_mul_f32 v[188:189], v[146:147], v[188:189]
	v_pk_mul_f32 v[190:191], v[148:149], v[190:191]
	v_pk_mul_f32 v[192:193], v[150:151], v[192:193]
	v_pk_mul_f32 v[194:195], v[152:153], v[194:195]
	v_pk_mul_f32 v[196:197], v[154:155], v[196:197]
	v_pk_mul_f32 v[218:219], v[156:157], v[218:219]
	v_pk_mul_f32 v[220:221], v[158:159], v[220:221]
	v_pk_mul_f32 v[222:223], v[160:161], v[222:223]
	v_exp_f32_e32 v188, v188
	v_exp_f32_e32 v189, v189
	v_exp_f32_e32 v190, v190
	v_exp_f32_e32 v191, v191
	v_exp_f32_e32 v192, v192
	v_exp_f32_e32 v193, v193
	v_exp_f32_e32 v194, v194
	v_exp_f32_e32 v195, v195
	v_exp_f32_e32 v196, v196
	v_exp_f32_e32 v197, v197
	v_exp_f32_e32 v218, v218
	v_exp_f32_e32 v219, v219
	v_exp_f32_e32 v220, v220
	v_exp_f32_e32 v221, v221
	v_exp_f32_e32 v222, v222
	v_exp_f32_e32 v223, v223
	v_pk_add_f32 v[188:189], v[188:189], v[182:183] op_sel_hi:[1,0]
	v_pk_add_f32 v[190:191], v[190:191], v[182:183] op_sel_hi:[1,0]
	v_pk_add_f32 v[192:193], v[192:193], v[182:183] op_sel_hi:[1,0]
	v_pk_add_f32 v[194:195], v[194:195], v[182:183] op_sel_hi:[1,0]
	v_pk_add_f32 v[196:197], v[196:197], v[182:183] op_sel_hi:[1,0]
	v_pk_add_f32 v[218:219], v[218:219], v[182:183] op_sel_hi:[1,0]
	v_pk_add_f32 v[220:221], v[220:221], v[182:183] op_sel_hi:[1,0]
	v_pk_add_f32 v[222:223], v[222:223], v[182:183] op_sel_hi:[1,0]
	v_rcp_f32_e32 v188, v188
	v_rcp_f32_e32 v189, v189
	v_rcp_f32_e32 v190, v190
	v_rcp_f32_e32 v191, v191
	v_rcp_f32_e32 v192, v192
	v_rcp_f32_e32 v193, v193
	v_rcp_f32_e32 v194, v194
	v_rcp_f32_e32 v195, v195
	v_rcp_f32_e32 v196, v196
	v_rcp_f32_e32 v197, v197
	v_rcp_f32_e32 v218, v218
	v_rcp_f32_e32 v219, v219
	v_rcp_f32_e32 v220, v220
	v_rcp_f32_e32 v221, v221
	v_rcp_f32_e32 v222, v222
	v_rcp_f32_e32 v223, v223
	v_pk_mul_f32 v[188:189], v[146:147], v[188:189]
	v_pk_mul_f32 v[190:191], v[148:149], v[190:191]
	v_pk_mul_f32 v[192:193], v[150:151], v[192:193]
	v_pk_mul_f32 v[194:195], v[152:153], v[194:195]
	v_pk_mul_f32 v[196:197], v[154:155], v[196:197]
	v_pk_mul_f32 v[218:219], v[156:157], v[218:219]
	v_pk_mul_f32 v[220:221], v[158:159], v[220:221]
	v_pk_mul_f32 v[222:223], v[160:161], v[222:223]
	v_pk_mul_f32 v[188:189], v[188:189], v[130:131]
	v_pk_mul_f32 v[190:191], v[190:191], v[132:133]
	v_pk_mul_f32 v[192:193], v[192:193], v[134:135]
	v_pk_mul_f32 v[194:195], v[194:195], v[136:137]
	v_pk_mul_f32 v[196:197], v[196:197], v[138:139]
	v_pk_mul_f32 v[218:219], v[218:219], v[140:141]
	v_pk_mul_f32 v[220:221], v[220:221], v[142:143]
	v_pk_mul_f32 v[222:223], v[222:223], v[144:145]
	v_cvt_pk_bf16_f32 v188, v188, v189
	v_cvt_pk_bf16_f32 v190, v190, v191
	v_cvt_pk_bf16_f32 v192, v192, v193
	v_cvt_pk_bf16_f32 v194, v194, v195
	v_cvt_pk_bf16_f32 v196, v196, v197
	v_cvt_pk_bf16_f32 v218, v218, v219
	v_cvt_pk_bf16_f32 v220, v220, v221
	v_cvt_pk_bf16_f32 v222, v222, v223
	ds_write_b16 v224, v188 offset:7680
	ds_write_b16_d16_hi v224, v188 offset:7760
	ds_write_b16 v224, v190 offset:7840
	ds_write_b16_d16_hi v224, v190 offset:7920
	ds_write_b16 v224, v192 offset:8320
	ds_write_b16_d16_hi v224, v192 offset:8400
	ds_write_b16 v224, v194 offset:8480
	ds_write_b16_d16_hi v224, v194 offset:8560
	ds_write_b16 v224, v196 offset:8960
	ds_write_b16_d16_hi v224, v196 offset:9040
	ds_write_b16 v224, v218 offset:9120
	ds_write_b16_d16_hi v224, v218 offset:9200
	ds_write_b16 v224, v220 offset:9600
	ds_write_b16_d16_hi v224, v220 offset:9680
	ds_write_b16 v224, v222 offset:9760
	ds_write_b16_d16_hi v224, v222 offset:9840
.Lupe_done:
	s_lshl_b32 s15, s15, 7
	s_lshl_b32 s16, s16, 5
	s_lshl_b32 s48, s48, 7
	s_movk_i32 s22, 0x50
	v_lshlrev_b32_e32 v0, 3, v167
	v_and_b32_e32 v0, 24, v0
	v_bfe_u32 v3, v165, 2, 4
	v_or_b32_e32 v5, s15, v3
	s_waitcnt lgkmcnt(0)
	v_lshl_or_b32 v2, v0, 1, s0
	v_add_u32_e32 v4, s14, v5
	v_add_u32_e32 v5, -1, v5
	s_movk_i32 s0, 0xfe
	v_cmp_gt_u32_e32 vcc, s0, v5
	v_cmp_gt_u32_e64 s[36:37], s26, v4
	s_and_b64 s[18:19], vcc, s[36:37]
	v_lshlrev_b32_e32 v0, 1, v0
	s_and_saveexec_b64 s[2:3], s[18:19]
	s_cbranch_execz .LBB0_783
	v_mad_u32_u24 v5, v3, s22, v2
	ds_read_b128 v[6:9], v5
	v_mov_b64_e32 v[10:11], s[20:21]
	s_movk_i32 s0, 0x1600
	v_mad_u64_u32 v[4:5], s[18:19], v4, s0, v[10:11]
	s_ashr_i32 s49, s48, 31
	v_lshl_add_u64 v[4:5], s[48:49], 1, v[4:5]
	s_lshl_b32 s0, s16, 1
	v_lshl_add_u64 v[4:5], v[4:5], 0, s[0:1]
	v_lshl_add_u64 v[4:5], v[4:5], 0, v[0:1]
	s_waitcnt lgkmcnt(0)
	global_store_dwordx4 v[4:5], v[6:9], off
